# scan: first-half o reduce issued after step 17's operand reads (reads in flight under the reduce)
# speedup vs baseline: 1.0008x; 1.0008x over previous
; __device__ __forceinline__ void scan_unit(const Ctx& C0, const float* scn, int T, int quarter, const float* S0, float* Sout, unsigned char* obase, int mode) {
;     ...
;         for (int k = 0; k < nch; ++k) {
;             const unsigned aq = (unsigned)(size_t)(C.lds + (k & 1) * SLOT_B) + 16u * (unsigned)q, av = (unsigned)(size_t)(C.lds + (k & 1) * SLOT_B) + (320u + (unsigned)irow) * 4u;
;             float osel0, osel1;
;             asm volatile(SCAN_CHUNK_ASM : "+v"(S0x), "+v"(S1x), "+v"(S2x), "+v"(S3x), "=&v"(osel0), "=&v"(osel1) : "v"(aq), "v"(av), "v"(q) : SCAN_CHUNK_CLOBBERS, "memory");
.LBB0_685:
	ds_read_b128 v[164:167], v5 offset:0
	ds_read_b128 v[168:171], v5 offset:256
	ds_read_b128 v[172:175], v5 offset:512
	ds_read_b128 v[176:179], v5 offset:768
	ds_read_b128 v[180:183], v5 offset:1024
	ds_read_b32 v184, v9 offset:0
	ds_read_b128 v[186:189], v5 offset:1536
	ds_read_b128 v[190:193], v5 offset:1792
	ds_read_b128 v[194:197], v5 offset:2048
	ds_read_b128 v[198:201], v5 offset:2304
	ds_read_b128 v[202:205], v5 offset:2560
	ds_read_b32 v206, v9 offset:1536
	ds_read_b128 v[208:211], v5 offset:3072
	s_waitcnt lgkmcnt(12)
	v_pk_mul_f32 v[144:145], v[138:139], v[164:165]
	v_pk_fma_f32 v[144:145], v[140:141], v[166:167], v[144:145]
	v_add_f32 v146, v144, v145
	ds_read_b128 v[212:215], v5 offset:3328
	ds_read_b128 v[216:219], v5 offset:3584
	ds_read_b128 v[220:223], v5 offset:3840
	ds_read_b128 v[224:227], v5 offset:4096
	ds_read_b32 v228, v9 offset:3072
	ds_read_b128 v[230:233], v5 offset:4608
	v_add_f32_dpp v146, v146, v146 quad_perm:[1,0,3,2] row_mask:0xf bank_mask:0xf bound_ctrl:1
	s_nop 0
	s_nop 0
	v_add_f32_dpp v146, v146, v146 quad_perm:[2,3,0,1] row_mask:0xf bank_mask:0xf bound_ctrl:1
	s_waitcnt lgkmcnt(12)
	v_pk_mul_f32 v[176:177], v[176:177], v[184:185] op_sel_hi:[1,0]
	v_add_f32_dpp v146, v146, v146 row_half_mirror row_mask:0xf bank_mask:0xf bound_ctrl:1
	v_pk_mul_f32 v[178:179], v[178:179], v[184:185] op_sel_hi:[1,0]
	s_nop 0
	v_add_f32_dpp v146, v146, v146 row_mirror row_mask:0xf bank_mask:0xf bound_ctrl:1
	v_pk_fma_f32 v[176:177], v[146:147], v[168:169], v[176:177] op_sel_hi:[0,1,1] neg_lo:[1,0,0] neg_hi:[1,0,0]
	v_pk_fma_f32 v[178:179], v[146:147], v[170:171], v[178:179] op_sel_hi:[0,1,1] neg_lo:[1,0,0] neg_hi:[1,0,0]
	v_pk_fma_f32 v[138:139], v[138:139], v[172:173], v[176:177]
	v_pk_fma_f32 v[140:141], v[140:141], v[174:175], v[178:179]
	v_pk_mul_f32 v[144:145], v[138:139], v[186:187]
	v_pk_fma_f32 v[144:145], v[140:141], v[188:189], v[144:145]
	v_add_f32 v146, v144, v145
	ds_read_b128 v[234:237], v5 offset:4864
	ds_read_b128 v[238:241], v5 offset:5120
	ds_read_b128 v[242:245], v5 offset:5376
	ds_read_b128 v[246:249], v5 offset:5632
	ds_read_b32 v250, v9 offset:4608
	ds_read_b128 v[164:167], v5 offset:6144
	v_add_f32_dpp v146, v146, v146 quad_perm:[1,0,3,2] row_mask:0xf bank_mask:0xf bound_ctrl:1
	v_pk_mul_f32 v[180:181], v[138:139], v[180:181]
	v_pk_fma_f32 v[180:181], v[140:141], v[182:183], v[180:181]
	v_add_f32_dpp v146, v146, v146 quad_perm:[2,3,0,1] row_mask:0xf bank_mask:0xf bound_ctrl:1
	s_waitcnt lgkmcnt(12)
	v_pk_mul_f32 v[198:199], v[198:199], v[206:207] op_sel_hi:[1,0]
	v_add_f32_dpp v146, v146, v146 row_half_mirror row_mask:0xf bank_mask:0xf bound_ctrl:1
	v_pk_mul_f32 v[200:201], v[200:201], v[206:207] op_sel_hi:[1,0]
	v_add_f32 v148, v180, v181
	v_add_f32_dpp v146, v146, v146 row_mirror row_mask:0xf bank_mask:0xf bound_ctrl:1
	v_pk_fma_f32 v[198:199], v[146:147], v[190:191], v[198:199] op_sel_hi:[0,1,1] neg_lo:[1,0,0] neg_hi:[1,0,0]
	v_pk_fma_f32 v[200:201], v[146:147], v[192:193], v[200:201] op_sel_hi:[0,1,1] neg_lo:[1,0,0] neg_hi:[1,0,0]
	v_pk_fma_f32 v[138:139], v[138:139], v[194:195], v[198:199]
	v_pk_fma_f32 v[140:141], v[140:141], v[196:197], v[200:201]
	v_pk_mul_f32 v[144:145], v[138:139], v[208:209]
	v_pk_fma_f32 v[144:145], v[140:141], v[210:211], v[144:145]
	v_add_f32 v146, v144, v145
	ds_read_b128 v[168:171], v5 offset:6400
	ds_read_b128 v[172:175], v5 offset:6656
	ds_read_b128 v[176:179], v5 offset:6912
	ds_read_b128 v[180:183], v5 offset:7168
	ds_read_b32 v184, v9 offset:6144
	ds_read_b128 v[186:189], v5 offset:7680
	v_add_f32_dpp v146, v146, v146 quad_perm:[1,0,3,2] row_mask:0xf bank_mask:0xf bound_ctrl:1
	v_pk_mul_f32 v[202:203], v[138:139], v[202:203]
	v_pk_fma_f32 v[202:203], v[140:141], v[204:205], v[202:203]
	v_add_f32_dpp v146, v146, v146 quad_perm:[2,3,0,1] row_mask:0xf bank_mask:0xf bound_ctrl:1
	s_waitcnt lgkmcnt(12)
	v_pk_mul_f32 v[220:221], v[220:221], v[228:229] op_sel_hi:[1,0]
	v_add_f32_dpp v146, v146, v146 row_half_mirror row_mask:0xf bank_mask:0xf bound_ctrl:1
	v_pk_mul_f32 v[222:223], v[222:223], v[228:229] op_sel_hi:[1,0]
	v_add_f32 v149, v202, v203
	v_add_f32_dpp v146, v146, v146 row_mirror row_mask:0xf bank_mask:0xf bound_ctrl:1
	v_pk_fma_f32 v[220:221], v[146:147], v[212:213], v[220:221] op_sel_hi:[0,1,1] neg_lo:[1,0,0] neg_hi:[1,0,0]
	v_pk_fma_f32 v[222:223], v[146:147], v[214:215], v[222:223] op_sel_hi:[0,1,1] neg_lo:[1,0,0] neg_hi:[1,0,0]
	v_pk_fma_f32 v[138:139], v[138:139], v[216:217], v[220:221]
	v_pk_fma_f32 v[140:141], v[140:141], v[218:219], v[222:223]
	v_pk_mul_f32 v[144:145], v[138:139], v[230:231]
	v_pk_fma_f32 v[144:145], v[140:141], v[232:233], v[144:145]
	v_add_f32 v146, v144, v145
	ds_read_b128 v[190:193], v5 offset:7936
	ds_read_b128 v[194:197], v5 offset:8192
	ds_read_b128 v[198:201], v5 offset:8448
	ds_read_b128 v[202:205], v5 offset:8704
	ds_read_b32 v206, v9 offset:7680
	ds_read_b128 v[208:211], v5 offset:9216
	v_add_f32_dpp v146, v146, v146 quad_perm:[1,0,3,2] row_mask:0xf bank_mask:0xf bound_ctrl:1
	v_pk_mul_f32 v[224:225], v[138:139], v[224:225]
	v_pk_fma_f32 v[224:225], v[140:141], v[226:227], v[224:225]
	v_add_f32_dpp v146, v146, v146 quad_perm:[2,3,0,1] row_mask:0xf bank_mask:0xf bound_ctrl:1
	s_waitcnt lgkmcnt(12)
	v_pk_mul_f32 v[242:243], v[242:243], v[250:251] op_sel_hi:[1,0]
	v_add_f32_dpp v146, v146, v146 row_half_mirror row_mask:0xf bank_mask:0xf bound_ctrl:1
	v_pk_mul_f32 v[244:245], v[244:245], v[250:251] op_sel_hi:[1,0]
	v_add_f32 v150, v224, v225
	v_add_f32_dpp v146, v146, v146 row_mirror row_mask:0xf bank_mask:0xf bound_ctrl:1
	v_pk_fma_f32 v[242:243], v[146:147], v[234:235], v[242:243] op_sel_hi:[0,1,1] neg_lo:[1,0,0] neg_hi:[1,0,0]
	v_pk_fma_f32 v[244:245], v[146:147], v[236:237], v[244:245] op_sel_hi:[0,1,1] neg_lo:[1,0,0] neg_hi:[1,0,0]
	v_pk_fma_f32 v[138:139], v[138:139], v[238:239], v[242:243]
	v_pk_fma_f32 v[140:141], v[140:141], v[240:241], v[244:245]
	v_pk_mul_f32 v[144:145], v[138:139], v[164:165]
	v_pk_fma_f32 v[144:145], v[140:141], v[166:167], v[144:145]
	v_add_f32 v146, v144, v145
	ds_read_b128 v[212:215], v5 offset:9472
	ds_read_b128 v[216:219], v5 offset:9728
	ds_read_b128 v[220:223], v5 offset:9984
	ds_read_b128 v[224:227], v5 offset:10240
	ds_read_b32 v228, v9 offset:9216
	ds_read_b128 v[230:233], v5 offset:10752
	v_add_f32_dpp v146, v146, v146 quad_perm:[1,0,3,2] row_mask:0xf bank_mask:0xf bound_ctrl:1
	v_pk_mul_f32 v[246:247], v[138:139], v[246:247]
	v_pk_fma_f32 v[246:247], v[140:141], v[248:249], v[246:247]
	v_add_f32_dpp v146, v146, v146 quad_perm:[2,3,0,1] row_mask:0xf bank_mask:0xf bound_ctrl:1
	s_waitcnt lgkmcnt(12)
	v_pk_mul_f32 v[176:177], v[176:177], v[184:185] op_sel_hi:[1,0]
	v_add_f32_dpp v146, v146, v146 row_half_mirror row_mask:0xf bank_mask:0xf bound_ctrl:1
	v_pk_mul_f32 v[178:179], v[178:179], v[184:185] op_sel_hi:[1,0]
	v_add_f32 v151, v246, v247
	v_add_f32_dpp v146, v146, v146 row_mirror row_mask:0xf bank_mask:0xf bound_ctrl:1
	v_pk_fma_f32 v[176:177], v[146:147], v[168:169], v[176:177] op_sel_hi:[0,1,1] neg_lo:[1,0,0] neg_hi:[1,0,0]
	v_pk_fma_f32 v[178:179], v[146:147], v[170:171], v[178:179] op_sel_hi:[0,1,1] neg_lo:[1,0,0] neg_hi:[1,0,0]
	v_pk_fma_f32 v[138:139], v[138:139], v[172:173], v[176:177]
	v_pk_fma_f32 v[140:141], v[140:141], v[174:175], v[178:179]
	v_pk_mul_f32 v[144:145], v[138:139], v[186:187]
	v_pk_fma_f32 v[144:145], v[140:141], v[188:189], v[144:145]
	v_add_f32 v146, v144, v145
	ds_read_b128 v[234:237], v5 offset:11008
	ds_read_b128 v[238:241], v5 offset:11264
	ds_read_b128 v[242:245], v5 offset:11520
	ds_read_b128 v[246:249], v5 offset:11776
	ds_read_b32 v250, v9 offset:10752
	ds_read_b128 v[164:167], v5 offset:12288
	v_add_f32_dpp v146, v146, v146 quad_perm:[1,0,3,2] row_mask:0xf bank_mask:0xf bound_ctrl:1
	v_pk_mul_f32 v[180:181], v[138:139], v[180:181]
	v_pk_fma_f32 v[180:181], v[140:141], v[182:183], v[180:181]
	v_add_f32_dpp v146, v146, v146 quad_perm:[2,3,0,1] row_mask:0xf bank_mask:0xf bound_ctrl:1
	s_waitcnt lgkmcnt(12)
	v_pk_mul_f32 v[198:199], v[198:199], v[206:207] op_sel_hi:[1,0]
	v_add_f32_dpp v146, v146, v146 row_half_mirror row_mask:0xf bank_mask:0xf bound_ctrl:1
	v_pk_mul_f32 v[200:201], v[200:201], v[206:207] op_sel_hi:[1,0]
	v_add_f32 v152, v180, v181
	v_add_f32_dpp v146, v146, v146 row_mirror row_mask:0xf bank_mask:0xf bound_ctrl:1
	v_pk_fma_f32 v[198:199], v[146:147], v[190:191], v[198:199] op_sel_hi:[0,1,1] neg_lo:[1,0,0] neg_hi:[1,0,0]
	v_pk_fma_f32 v[200:201], v[146:147], v[192:193], v[200:201] op_sel_hi:[0,1,1] neg_lo:[1,0,0] neg_hi:[1,0,0]
	v_pk_fma_f32 v[138:139], v[138:139], v[194:195], v[198:199]
	v_pk_fma_f32 v[140:141], v[140:141], v[196:197], v[200:201]
	v_pk_mul_f32 v[144:145], v[138:139], v[208:209]
	v_pk_fma_f32 v[144:145], v[140:141], v[210:211], v[144:145]
	v_add_f32 v146, v144, v145
	ds_read_b128 v[168:171], v5 offset:12544
	ds_read_b128 v[172:175], v5 offset:12800
	ds_read_b128 v[176:179], v5 offset:13056
	ds_read_b128 v[180:183], v5 offset:13312
	ds_read_b32 v184, v9 offset:12288
	ds_read_b128 v[186:189], v5 offset:13824
	v_add_f32_dpp v146, v146, v146 quad_perm:[1,0,3,2] row_mask:0xf bank_mask:0xf bound_ctrl:1
	v_pk_mul_f32 v[202:203], v[138:139], v[202:203]
	v_pk_fma_f32 v[202:203], v[140:141], v[204:205], v[202:203]
	v_add_f32_dpp v146, v146, v146 quad_perm:[2,3,0,1] row_mask:0xf bank_mask:0xf bound_ctrl:1
	s_waitcnt lgkmcnt(12)
	v_pk_mul_f32 v[220:221], v[220:221], v[228:229] op_sel_hi:[1,0]
	v_add_f32_dpp v146, v146, v146 row_half_mirror row_mask:0xf bank_mask:0xf bound_ctrl:1
	v_pk_mul_f32 v[222:223], v[222:223], v[228:229] op_sel_hi:[1,0]
	v_add_f32 v153, v202, v203
	v_add_f32_dpp v146, v146, v146 row_mirror row_mask:0xf bank_mask:0xf bound_ctrl:1
	v_pk_fma_f32 v[220:221], v[146:147], v[212:213], v[220:221] op_sel_hi:[0,1,1] neg_lo:[1,0,0] neg_hi:[1,0,0]
	v_pk_fma_f32 v[222:223], v[146:147], v[214:215], v[222:223] op_sel_hi:[0,1,1] neg_lo:[1,0,0] neg_hi:[1,0,0]
	v_pk_fma_f32 v[138:139], v[138:139], v[216:217], v[220:221]
	v_pk_fma_f32 v[140:141], v[140:141], v[218:219], v[222:223]
	v_pk_mul_f32 v[144:145], v[138:139], v[230:231]
	v_pk_fma_f32 v[144:145], v[140:141], v[232:233], v[144:145]
	v_add_f32 v146, v144, v145
	ds_read_b128 v[190:193], v5 offset:14080
	ds_read_b128 v[194:197], v5 offset:14336
	ds_read_b128 v[198:201], v5 offset:14592
	ds_read_b128 v[202:205], v5 offset:14848
	ds_read_b32 v206, v9 offset:13824
	ds_read_b128 v[208:211], v5 offset:15360
	v_add_f32_dpp v146, v146, v146 quad_perm:[1,0,3,2] row_mask:0xf bank_mask:0xf bound_ctrl:1
	v_pk_mul_f32 v[224:225], v[138:139], v[224:225]
	v_pk_fma_f32 v[224:225], v[140:141], v[226:227], v[224:225]
	v_add_f32_dpp v146, v146, v146 quad_perm:[2,3,0,1] row_mask:0xf bank_mask:0xf bound_ctrl:1
	s_waitcnt lgkmcnt(12)
	v_pk_mul_f32 v[242:243], v[242:243], v[250:251] op_sel_hi:[1,0]
	v_add_f32_dpp v146, v146, v146 row_half_mirror row_mask:0xf bank_mask:0xf bound_ctrl:1
	v_pk_mul_f32 v[244:245], v[244:245], v[250:251] op_sel_hi:[1,0]
	v_add_f32 v154, v224, v225
	v_add_f32_dpp v146, v146, v146 row_mirror row_mask:0xf bank_mask:0xf bound_ctrl:1
	v_pk_fma_f32 v[242:243], v[146:147], v[234:235], v[242:243] op_sel_hi:[0,1,1] neg_lo:[1,0,0] neg_hi:[1,0,0]
	v_pk_fma_f32 v[244:245], v[146:147], v[236:237], v[244:245] op_sel_hi:[0,1,1] neg_lo:[1,0,0] neg_hi:[1,0,0]
	v_pk_fma_f32 v[138:139], v[138:139], v[238:239], v[242:243]
	v_pk_fma_f32 v[140:141], v[140:141], v[240:241], v[244:245]
	v_pk_mul_f32 v[144:145], v[138:139], v[164:165]
	v_pk_fma_f32 v[144:145], v[140:141], v[166:167], v[144:145]
	v_add_f32 v146, v144, v145
	ds_read_b128 v[212:215], v5 offset:15616
	ds_read_b128 v[216:219], v5 offset:15872
	ds_read_b128 v[220:223], v5 offset:16128
	ds_read_b128 v[224:227], v5 offset:16384
	ds_read_b32 v228, v9 offset:15360
	ds_read_b128 v[230:233], v5 offset:16896
	v_add_f32_dpp v146, v146, v146 quad_perm:[1,0,3,2] row_mask:0xf bank_mask:0xf bound_ctrl:1
	v_pk_mul_f32 v[246:247], v[138:139], v[246:247]
	v_pk_fma_f32 v[246:247], v[140:141], v[248:249], v[246:247]
	v_add_f32_dpp v146, v146, v146 quad_perm:[2,3,0,1] row_mask:0xf bank_mask:0xf bound_ctrl:1
	s_waitcnt lgkmcnt(12)
	v_pk_mul_f32 v[176:177], v[176:177], v[184:185] op_sel_hi:[1,0]
	v_add_f32_dpp v146, v146, v146 row_half_mirror row_mask:0xf bank_mask:0xf bound_ctrl:1
	v_pk_mul_f32 v[178:179], v[178:179], v[184:185] op_sel_hi:[1,0]
	v_add_f32 v155, v246, v247
	v_add_f32_dpp v146, v146, v146 row_mirror row_mask:0xf bank_mask:0xf bound_ctrl:1
	v_pk_fma_f32 v[176:177], v[146:147], v[168:169], v[176:177] op_sel_hi:[0,1,1] neg_lo:[1,0,0] neg_hi:[1,0,0]
	v_pk_fma_f32 v[178:179], v[146:147], v[170:171], v[178:179] op_sel_hi:[0,1,1] neg_lo:[1,0,0] neg_hi:[1,0,0]
	v_pk_fma_f32 v[138:139], v[138:139], v[172:173], v[176:177]
	v_pk_fma_f32 v[140:141], v[140:141], v[174:175], v[178:179]
	v_pk_mul_f32 v[144:145], v[138:139], v[186:187]
	v_pk_fma_f32 v[144:145], v[140:141], v[188:189], v[144:145]
	v_add_f32 v146, v144, v145
	ds_read_b128 v[234:237], v5 offset:17152
	ds_read_b128 v[238:241], v5 offset:17408
	ds_read_b128 v[242:245], v5 offset:17664
	ds_read_b128 v[246:249], v5 offset:17920
	ds_read_b32 v250, v9 offset:16896
	ds_read_b128 v[164:167], v5 offset:18432
	v_add_f32_dpp v146, v146, v146 quad_perm:[1,0,3,2] row_mask:0xf bank_mask:0xf bound_ctrl:1
	v_pk_mul_f32 v[180:181], v[138:139], v[180:181]
	v_pk_fma_f32 v[180:181], v[140:141], v[182:183], v[180:181]
	v_add_f32_dpp v146, v146, v146 quad_perm:[2,3,0,1] row_mask:0xf bank_mask:0xf bound_ctrl:1
	s_waitcnt lgkmcnt(12)
	v_pk_mul_f32 v[198:199], v[198:199], v[206:207] op_sel_hi:[1,0]
	v_add_f32_dpp v146, v146, v146 row_half_mirror row_mask:0xf bank_mask:0xf bound_ctrl:1
	v_pk_mul_f32 v[200:201], v[200:201], v[206:207] op_sel_hi:[1,0]
	v_add_f32 v156, v180, v181
	v_add_f32_dpp v146, v146, v146 row_mirror row_mask:0xf bank_mask:0xf bound_ctrl:1
	v_pk_fma_f32 v[198:199], v[146:147], v[190:191], v[198:199] op_sel_hi:[0,1,1] neg_lo:[1,0,0] neg_hi:[1,0,0]
	v_pk_fma_f32 v[200:201], v[146:147], v[192:193], v[200:201] op_sel_hi:[0,1,1] neg_lo:[1,0,0] neg_hi:[1,0,0]
	v_pk_fma_f32 v[138:139], v[138:139], v[194:195], v[198:199]
	v_pk_fma_f32 v[140:141], v[140:141], v[196:197], v[200:201]
	v_pk_mul_f32 v[144:145], v[138:139], v[208:209]
	v_pk_fma_f32 v[144:145], v[140:141], v[210:211], v[144:145]
	v_add_f32 v146, v144, v145
	ds_read_b128 v[168:171], v5 offset:18688
	ds_read_b128 v[172:175], v5 offset:18944
	ds_read_b128 v[176:179], v5 offset:19200
	ds_read_b128 v[180:183], v5 offset:19456
	ds_read_b32 v184, v9 offset:18432
	ds_read_b128 v[186:189], v5 offset:19968
	v_add_f32_dpp v146, v146, v146 quad_perm:[1,0,3,2] row_mask:0xf bank_mask:0xf bound_ctrl:1
	v_pk_mul_f32 v[202:203], v[138:139], v[202:203]
	v_pk_fma_f32 v[202:203], v[140:141], v[204:205], v[202:203]
	v_add_f32_dpp v146, v146, v146 quad_perm:[2,3,0,1] row_mask:0xf bank_mask:0xf bound_ctrl:1
	s_waitcnt lgkmcnt(12)
	v_pk_mul_f32 v[220:221], v[220:221], v[228:229] op_sel_hi:[1,0]
	v_add_f32_dpp v146, v146, v146 row_half_mirror row_mask:0xf bank_mask:0xf bound_ctrl:1
	v_pk_mul_f32 v[222:223], v[222:223], v[228:229] op_sel_hi:[1,0]
	v_add_f32 v157, v202, v203
	v_add_f32_dpp v146, v146, v146 row_mirror row_mask:0xf bank_mask:0xf bound_ctrl:1
	v_pk_fma_f32 v[220:221], v[146:147], v[212:213], v[220:221] op_sel_hi:[0,1,1] neg_lo:[1,0,0] neg_hi:[1,0,0]
	v_pk_fma_f32 v[222:223], v[146:147], v[214:215], v[222:223] op_sel_hi:[0,1,1] neg_lo:[1,0,0] neg_hi:[1,0,0]
	v_pk_fma_f32 v[138:139], v[138:139], v[216:217], v[220:221]
	v_pk_fma_f32 v[140:141], v[140:141], v[218:219], v[222:223]
	v_pk_mul_f32 v[144:145], v[138:139], v[230:231]
	v_pk_fma_f32 v[144:145], v[140:141], v[232:233], v[144:145]
	v_add_f32 v146, v144, v145
	ds_read_b128 v[190:193], v5 offset:20224
	ds_read_b128 v[194:197], v5 offset:20480
	ds_read_b128 v[198:201], v5 offset:20736
	ds_read_b128 v[202:205], v5 offset:20992
	ds_read_b32 v206, v9 offset:19968
	ds_read_b128 v[208:211], v5 offset:21504
	v_add_f32_dpp v146, v146, v146 quad_perm:[1,0,3,2] row_mask:0xf bank_mask:0xf bound_ctrl:1
	v_pk_mul_f32 v[224:225], v[138:139], v[224:225]
	v_pk_fma_f32 v[224:225], v[140:141], v[226:227], v[224:225]
	v_add_f32_dpp v146, v146, v146 quad_perm:[2,3,0,1] row_mask:0xf bank_mask:0xf bound_ctrl:1
	s_waitcnt lgkmcnt(12)
	v_pk_mul_f32 v[242:243], v[242:243], v[250:251] op_sel_hi:[1,0]
	v_add_f32_dpp v146, v146, v146 row_half_mirror row_mask:0xf bank_mask:0xf bound_ctrl:1
	v_pk_mul_f32 v[244:245], v[244:245], v[250:251] op_sel_hi:[1,0]
	v_add_f32 v158, v224, v225
	v_add_f32_dpp v146, v146, v146 row_mirror row_mask:0xf bank_mask:0xf bound_ctrl:1
	v_pk_fma_f32 v[242:243], v[146:147], v[234:235], v[242:243] op_sel_hi:[0,1,1] neg_lo:[1,0,0] neg_hi:[1,0,0]
	v_pk_fma_f32 v[244:245], v[146:147], v[236:237], v[244:245] op_sel_hi:[0,1,1] neg_lo:[1,0,0] neg_hi:[1,0,0]
	v_pk_fma_f32 v[138:139], v[138:139], v[238:239], v[242:243]
	v_pk_fma_f32 v[140:141], v[140:141], v[240:241], v[244:245]
	v_pk_mul_f32 v[144:145], v[138:139], v[164:165]
	v_pk_fma_f32 v[144:145], v[140:141], v[166:167], v[144:145]
	v_add_f32 v146, v144, v145
	ds_read_b128 v[212:215], v5 offset:21760
	ds_read_b128 v[216:219], v5 offset:22016
	ds_read_b128 v[220:223], v5 offset:22272
	ds_read_b128 v[224:227], v5 offset:22528
	ds_read_b32 v228, v9 offset:21504
	ds_read_b128 v[230:233], v5 offset:23040
	v_add_f32_dpp v146, v146, v146 quad_perm:[1,0,3,2] row_mask:0xf bank_mask:0xf bound_ctrl:1
	v_pk_mul_f32 v[246:247], v[138:139], v[246:247]
	v_pk_fma_f32 v[246:247], v[140:141], v[248:249], v[246:247]
	v_add_f32_dpp v146, v146, v146 quad_perm:[2,3,0,1] row_mask:0xf bank_mask:0xf bound_ctrl:1
	s_waitcnt lgkmcnt(12)
	v_pk_mul_f32 v[176:177], v[176:177], v[184:185] op_sel_hi:[1,0]
	v_add_f32_dpp v146, v146, v146 row_half_mirror row_mask:0xf bank_mask:0xf bound_ctrl:1
	v_pk_mul_f32 v[178:179], v[178:179], v[184:185] op_sel_hi:[1,0]
	v_add_f32 v159, v246, v247
	v_add_f32_dpp v146, v146, v146 row_mirror row_mask:0xf bank_mask:0xf bound_ctrl:1
	v_pk_fma_f32 v[176:177], v[146:147], v[168:169], v[176:177] op_sel_hi:[0,1,1] neg_lo:[1,0,0] neg_hi:[1,0,0]
	v_pk_fma_f32 v[178:179], v[146:147], v[170:171], v[178:179] op_sel_hi:[0,1,1] neg_lo:[1,0,0] neg_hi:[1,0,0]
	v_pk_fma_f32 v[138:139], v[138:139], v[172:173], v[176:177]
	v_pk_fma_f32 v[140:141], v[140:141], v[174:175], v[178:179]
	v_pk_mul_f32 v[144:145], v[138:139], v[186:187]
	v_pk_fma_f32 v[144:145], v[140:141], v[188:189], v[144:145]
	v_add_f32 v146, v144, v145
	ds_read_b128 v[234:237], v5 offset:23296
	ds_read_b128 v[238:241], v5 offset:23552
	ds_read_b128 v[242:245], v5 offset:23808
	ds_read_b128 v[246:249], v5 offset:24064
	ds_read_b32 v250, v9 offset:23040
	ds_read_b128 v[164:167], v5 offset:24576
	v_add_f32_dpp v146, v146, v146 quad_perm:[1,0,3,2] row_mask:0xf bank_mask:0xf bound_ctrl:1
	v_pk_mul_f32 v[180:181], v[138:139], v[180:181]
	v_pk_fma_f32 v[180:181], v[140:141], v[182:183], v[180:181]
	v_add_f32_dpp v146, v146, v146 quad_perm:[2,3,0,1] row_mask:0xf bank_mask:0xf bound_ctrl:1
	s_waitcnt lgkmcnt(12)
	v_pk_mul_f32 v[198:199], v[198:199], v[206:207] op_sel_hi:[1,0]
	v_add_f32_dpp v146, v146, v146 row_half_mirror row_mask:0xf bank_mask:0xf bound_ctrl:1
	v_pk_mul_f32 v[200:201], v[200:201], v[206:207] op_sel_hi:[1,0]
	v_add_f32 v160, v180, v181
	v_add_f32_dpp v146, v146, v146 row_mirror row_mask:0xf bank_mask:0xf bound_ctrl:1
	v_pk_fma_f32 v[198:199], v[146:147], v[190:191], v[198:199] op_sel_hi:[0,1,1] neg_lo:[1,0,0] neg_hi:[1,0,0]
	v_pk_fma_f32 v[200:201], v[146:147], v[192:193], v[200:201] op_sel_hi:[0,1,1] neg_lo:[1,0,0] neg_hi:[1,0,0]
	v_pk_fma_f32 v[138:139], v[138:139], v[194:195], v[198:199]
	v_pk_fma_f32 v[140:141], v[140:141], v[196:197], v[200:201]
	v_pk_mul_f32 v[144:145], v[138:139], v[208:209]
	v_pk_fma_f32 v[144:145], v[140:141], v[210:211], v[144:145]
	v_add_f32 v146, v144, v145
	ds_read_b128 v[168:171], v5 offset:24832
	ds_read_b128 v[172:175], v5 offset:25088
	ds_read_b128 v[176:179], v5 offset:25344
	ds_read_b128 v[180:183], v5 offset:25600
	ds_read_b32 v184, v9 offset:24576
	ds_read_b128 v[186:189], v5 offset:26112
	v_add_f32_dpp v146, v146, v146 quad_perm:[1,0,3,2] row_mask:0xf bank_mask:0xf bound_ctrl:1
	v_pk_mul_f32 v[202:203], v[138:139], v[202:203]
	v_pk_fma_f32 v[202:203], v[140:141], v[204:205], v[202:203]
	v_add_f32_dpp v146, v146, v146 quad_perm:[2,3,0,1] row_mask:0xf bank_mask:0xf bound_ctrl:1
	s_waitcnt lgkmcnt(12)
	v_pk_mul_f32 v[220:221], v[220:221], v[228:229] op_sel_hi:[1,0]
	v_add_f32_dpp v146, v146, v146 row_half_mirror row_mask:0xf bank_mask:0xf bound_ctrl:1
	v_pk_mul_f32 v[222:223], v[222:223], v[228:229] op_sel_hi:[1,0]
	v_add_f32 v161, v202, v203
	v_add_f32_dpp v146, v146, v146 row_mirror row_mask:0xf bank_mask:0xf bound_ctrl:1
	v_pk_fma_f32 v[220:221], v[146:147], v[212:213], v[220:221] op_sel_hi:[0,1,1] neg_lo:[1,0,0] neg_hi:[1,0,0]
	v_pk_fma_f32 v[222:223], v[146:147], v[214:215], v[222:223] op_sel_hi:[0,1,1] neg_lo:[1,0,0] neg_hi:[1,0,0]
	v_pk_fma_f32 v[138:139], v[138:139], v[216:217], v[220:221]
	v_pk_fma_f32 v[140:141], v[140:141], v[218:219], v[222:223]
	v_pk_mul_f32 v[144:145], v[138:139], v[230:231]
	v_pk_fma_f32 v[144:145], v[140:141], v[232:233], v[144:145]
	v_add_f32 v146, v144, v145
	ds_read_b128 v[190:193], v5 offset:26368
	ds_read_b128 v[194:197], v5 offset:26624
	ds_read_b128 v[198:201], v5 offset:26880
	ds_read_b128 v[202:205], v5 offset:27136
	ds_read_b32 v206, v9 offset:26112
	ds_read_b128 v[208:211], v5 offset:27648
	v_add_f32_dpp v146, v146, v146 quad_perm:[1,0,3,2] row_mask:0xf bank_mask:0xf bound_ctrl:1
	v_pk_mul_f32 v[224:225], v[138:139], v[224:225]
	v_pk_fma_f32 v[224:225], v[140:141], v[226:227], v[224:225]
	v_add_f32_dpp v146, v146, v146 quad_perm:[2,3,0,1] row_mask:0xf bank_mask:0xf bound_ctrl:1
	s_waitcnt lgkmcnt(12)
	v_pk_mul_f32 v[242:243], v[242:243], v[250:251] op_sel_hi:[1,0]
	v_add_f32_dpp v146, v146, v146 row_half_mirror row_mask:0xf bank_mask:0xf bound_ctrl:1
	v_pk_mul_f32 v[244:245], v[244:245], v[250:251] op_sel_hi:[1,0]
	v_add_f32 v162, v224, v225
	v_add_f32_dpp v146, v146, v146 row_mirror row_mask:0xf bank_mask:0xf bound_ctrl:1
	v_pk_fma_f32 v[242:243], v[146:147], v[234:235], v[242:243] op_sel_hi:[0,1,1] neg_lo:[1,0,0] neg_hi:[1,0,0]
	v_pk_fma_f32 v[244:245], v[146:147], v[236:237], v[244:245] op_sel_hi:[0,1,1] neg_lo:[1,0,0] neg_hi:[1,0,0]
	v_pk_fma_f32 v[138:139], v[138:139], v[238:239], v[242:243]
	v_pk_fma_f32 v[140:141], v[140:141], v[240:241], v[244:245]
	v_pk_mul_f32 v[144:145], v[138:139], v[164:165]
	v_pk_fma_f32 v[144:145], v[140:141], v[166:167], v[144:145]
	v_add_f32 v146, v144, v145
	ds_read_b128 v[212:215], v5 offset:27904
	ds_read_b128 v[216:219], v5 offset:28160
	ds_read_b128 v[220:223], v5 offset:28416
	ds_read_b128 v[224:227], v5 offset:28672
	ds_read_b32 v228, v9 offset:27648
	ds_read_b128 v[230:233], v5 offset:29184
	v_add_f32_dpp v146, v146, v146 quad_perm:[1,0,3,2] row_mask:0xf bank_mask:0xf bound_ctrl:1
	v_pk_mul_f32 v[246:247], v[138:139], v[246:247]
	v_pk_fma_f32 v[246:247], v[140:141], v[248:249], v[246:247]
	v_add_f32_dpp v146, v146, v146 quad_perm:[2,3,0,1] row_mask:0xf bank_mask:0xf bound_ctrl:1
	s_waitcnt lgkmcnt(12)
	v_pk_mul_f32 v[176:177], v[176:177], v[184:185] op_sel_hi:[1,0]
	v_add_f32_dpp v146, v146, v146 row_half_mirror row_mask:0xf bank_mask:0xf bound_ctrl:1
	v_pk_mul_f32 v[178:179], v[178:179], v[184:185] op_sel_hi:[1,0]
	v_add_f32 v163, v246, v247
	v_add_f32_dpp v146, v146, v146 row_mirror row_mask:0xf bank_mask:0xf bound_ctrl:1
	v_pk_fma_f32 v[176:177], v[146:147], v[168:169], v[176:177] op_sel_hi:[0,1,1] neg_lo:[1,0,0] neg_hi:[1,0,0]
	v_pk_fma_f32 v[178:179], v[146:147], v[170:171], v[178:179] op_sel_hi:[0,1,1] neg_lo:[1,0,0] neg_hi:[1,0,0]
	v_pk_fma_f32 v[138:139], v[138:139], v[172:173], v[176:177]
	v_pk_fma_f32 v[140:141], v[140:141], v[174:175], v[178:179]
	v_pk_mul_f32 v[144:145], v[138:139], v[186:187]
	v_pk_fma_f32 v[144:145], v[140:141], v[188:189], v[144:145]
	v_add_f32 v146, v144, v145
	ds_read_b128 v[234:237], v5 offset:29440
	ds_read_b128 v[238:241], v5 offset:29696
	ds_read_b128 v[242:245], v5 offset:29952
	ds_read_b128 v[246:249], v5 offset:30208
	ds_read_b32 v250, v9 offset:29184
	ds_read_b128 v[164:167], v5 offset:30720
	v_add_f32_dpp v102, v148, v148 row_mirror row_mask:0xf bank_mask:0x3 bound_ctrl:1
	v_add_f32_dpp v102, v156, v156 row_mirror row_mask:0xf bank_mask:0xc bound_ctrl:1
	v_add_f32_dpp v103, v149, v149 row_mirror row_mask:0xf bank_mask:0x3 bound_ctrl:1
	v_add_f32_dpp v103, v157, v157 row_mirror row_mask:0xf bank_mask:0xc bound_ctrl:1
	v_add_f32_dpp v104, v150, v150 row_mirror row_mask:0xf bank_mask:0x3 bound_ctrl:1
	v_add_f32_dpp v104, v158, v158 row_mirror row_mask:0xf bank_mask:0xc bound_ctrl:1
	v_add_f32_dpp v105, v151, v151 row_mirror row_mask:0xf bank_mask:0x3 bound_ctrl:1
	v_add_f32_dpp v105, v159, v159 row_mirror row_mask:0xf bank_mask:0xc bound_ctrl:1
	v_add_f32_dpp v106, v152, v152 row_mirror row_mask:0xf bank_mask:0x3 bound_ctrl:1
	v_add_f32_dpp v106, v160, v160 row_mirror row_mask:0xf bank_mask:0xc bound_ctrl:1
	v_add_f32_dpp v107, v153, v153 row_mirror row_mask:0xf bank_mask:0x3 bound_ctrl:1
	v_add_f32_dpp v107, v161, v161 row_mirror row_mask:0xf bank_mask:0xc bound_ctrl:1
	v_add_f32_dpp v108, v154, v154 row_mirror row_mask:0xf bank_mask:0x3 bound_ctrl:1
	v_add_f32_dpp v108, v162, v162 row_mirror row_mask:0xf bank_mask:0xc bound_ctrl:1
	v_add_f32_dpp v109, v155, v155 row_mirror row_mask:0xf bank_mask:0x3 bound_ctrl:1
	v_add_f32_dpp v109, v163, v163 row_mirror row_mask:0xf bank_mask:0xc bound_ctrl:1
	v_add_f32_dpp v110, v102, v102 row_half_mirror row_mask:0xf bank_mask:0x5 bound_ctrl:1
	v_add_f32_dpp v110, v106, v106 row_half_mirror row_mask:0xf bank_mask:0xa bound_ctrl:1
	v_add_f32_dpp v111, v103, v103 row_half_mirror row_mask:0xf bank_mask:0x5 bound_ctrl:1
	v_add_f32_dpp v111, v107, v107 row_half_mirror row_mask:0xf bank_mask:0xa bound_ctrl:1
	v_add_f32_dpp v112, v104, v104 row_half_mirror row_mask:0xf bank_mask:0x5 bound_ctrl:1
	v_add_f32_dpp v112, v108, v108 row_half_mirror row_mask:0xf bank_mask:0xa bound_ctrl:1
	v_add_f32_dpp v113, v105, v105 row_half_mirror row_mask:0xf bank_mask:0x5 bound_ctrl:1
	v_add_f32_dpp v113, v109, v109 row_half_mirror row_mask:0xf bank_mask:0xa bound_ctrl:1
	s_mov_b32 vcc_lo, 0xcccccccc
	s_mov_b32 vcc_hi, 0xcccccccc
	v_cndmask_b32 v116, v112, v110, vcc
	v_cndmask_b32 v117, v113, v111, vcc
	v_cndmask_b32 v114, v110, v112, vcc
	v_cndmask_b32 v115, v111, v113, vcc
	v_add_f32_dpp v114, v116, v114 quad_perm:[2,3,0,1] row_mask:0xf bank_mask:0xf bound_ctrl:1
	v_add_f32_dpp v115, v117, v115 quad_perm:[2,3,0,1] row_mask:0xf bank_mask:0xf bound_ctrl:1
	s_mov_b32 vcc_lo, 0xaaaaaaaa
	s_mov_b32 vcc_hi, 0xaaaaaaaa
	v_cndmask_b32 v116, v115, v114, vcc
	v_cndmask_b32 v117, v114, v115, vcc
	s_nop 0
	v_add_f32_dpp v18, v116, v117 quad_perm:[1,0,3,2] row_mask:0xf bank_mask:0xf bound_ctrl:1
	v_add_f32_dpp v146, v146, v146 quad_perm:[1,0,3,2] row_mask:0xf bank_mask:0xf bound_ctrl:1
	v_pk_mul_f32 v[180:181], v[138:139], v[180:181]
	v_pk_fma_f32 v[180:181], v[140:141], v[182:183], v[180:181]
	v_add_f32_dpp v146, v146, v146 quad_perm:[2,3,0,1] row_mask:0xf bank_mask:0xf bound_ctrl:1
	s_waitcnt lgkmcnt(12)
	v_pk_mul_f32 v[198:199], v[198:199], v[206:207] op_sel_hi:[1,0]
	v_add_f32_dpp v146, v146, v146 row_half_mirror row_mask:0xf bank_mask:0xf bound_ctrl:1
	v_pk_mul_f32 v[200:201], v[200:201], v[206:207] op_sel_hi:[1,0]
	v_add_f32 v148, v180, v181
	v_add_f32_dpp v146, v146, v146 row_mirror row_mask:0xf bank_mask:0xf bound_ctrl:1
	v_pk_fma_f32 v[198:199], v[146:147], v[190:191], v[198:199] op_sel_hi:[0,1,1] neg_lo:[1,0,0] neg_hi:[1,0,0]
	v_pk_fma_f32 v[200:201], v[146:147], v[192:193], v[200:201] op_sel_hi:[0,1,1] neg_lo:[1,0,0] neg_hi:[1,0,0]
	v_pk_fma_f32 v[138:139], v[138:139], v[194:195], v[198:199]
	v_pk_fma_f32 v[140:141], v[140:141], v[196:197], v[200:201]
	v_pk_mul_f32 v[144:145], v[138:139], v[208:209]
	v_pk_fma_f32 v[144:145], v[140:141], v[210:211], v[144:145]
	v_add_f32 v146, v144, v145
	ds_read_b128 v[168:171], v5 offset:30976
	ds_read_b128 v[172:175], v5 offset:31232
	ds_read_b128 v[176:179], v5 offset:31488
	ds_read_b128 v[180:183], v5 offset:31744
	ds_read_b32 v184, v9 offset:30720
	ds_read_b128 v[186:189], v5 offset:32256
	v_add_f32_dpp v146, v146, v146 quad_perm:[1,0,3,2] row_mask:0xf bank_mask:0xf bound_ctrl:1
	v_pk_mul_f32 v[202:203], v[138:139], v[202:203]
	v_pk_fma_f32 v[202:203], v[140:141], v[204:205], v[202:203]
	v_add_f32_dpp v146, v146, v146 quad_perm:[2,3,0,1] row_mask:0xf bank_mask:0xf bound_ctrl:1
	s_waitcnt lgkmcnt(12)
	v_pk_mul_f32 v[220:221], v[220:221], v[228:229] op_sel_hi:[1,0]
	v_add_f32_dpp v146, v146, v146 row_half_mirror row_mask:0xf bank_mask:0xf bound_ctrl:1
	v_pk_mul_f32 v[222:223], v[222:223], v[228:229] op_sel_hi:[1,0]
	v_add_f32 v149, v202, v203
	v_add_f32_dpp v146, v146, v146 row_mirror row_mask:0xf bank_mask:0xf bound_ctrl:1
	v_pk_fma_f32 v[220:221], v[146:147], v[212:213], v[220:221] op_sel_hi:[0,1,1] neg_lo:[1,0,0] neg_hi:[1,0,0]
	v_pk_fma_f32 v[222:223], v[146:147], v[214:215], v[222:223] op_sel_hi:[0,1,1] neg_lo:[1,0,0] neg_hi:[1,0,0]
	v_pk_fma_f32 v[138:139], v[138:139], v[216:217], v[220:221]
	v_pk_fma_f32 v[140:141], v[140:141], v[218:219], v[222:223]
	v_pk_mul_f32 v[144:145], v[138:139], v[230:231]
	v_pk_fma_f32 v[144:145], v[140:141], v[232:233], v[144:145]
	v_add_f32 v146, v144, v145
	ds_read_b128 v[190:193], v5 offset:32512
	ds_read_b128 v[194:197], v5 offset:32768
	ds_read_b128 v[198:201], v5 offset:33024
	ds_read_b128 v[202:205], v5 offset:33280
	ds_read_b32 v206, v9 offset:32256
	ds_read_b128 v[208:211], v5 offset:33792
	v_add_f32_dpp v146, v146, v146 quad_perm:[1,0,3,2] row_mask:0xf bank_mask:0xf bound_ctrl:1
	v_pk_mul_f32 v[224:225], v[138:139], v[224:225]
	v_pk_fma_f32 v[224:225], v[140:141], v[226:227], v[224:225]
	v_add_f32_dpp v146, v146, v146 quad_perm:[2,3,0,1] row_mask:0xf bank_mask:0xf bound_ctrl:1
	s_waitcnt lgkmcnt(12)
	v_pk_mul_f32 v[242:243], v[242:243], v[250:251] op_sel_hi:[1,0]
	v_add_f32_dpp v146, v146, v146 row_half_mirror row_mask:0xf bank_mask:0xf bound_ctrl:1
	v_pk_mul_f32 v[244:245], v[244:245], v[250:251] op_sel_hi:[1,0]
	v_add_f32 v150, v224, v225
	v_add_f32_dpp v146, v146, v146 row_mirror row_mask:0xf bank_mask:0xf bound_ctrl:1
	v_pk_fma_f32 v[242:243], v[146:147], v[234:235], v[242:243] op_sel_hi:[0,1,1] neg_lo:[1,0,0] neg_hi:[1,0,0]
	v_pk_fma_f32 v[244:245], v[146:147], v[236:237], v[244:245] op_sel_hi:[0,1,1] neg_lo:[1,0,0] neg_hi:[1,0,0]
	v_pk_fma_f32 v[138:139], v[138:139], v[238:239], v[242:243]
	v_pk_fma_f32 v[140:141], v[140:141], v[240:241], v[244:245]
	v_pk_mul_f32 v[144:145], v[138:139], v[164:165]
	v_pk_fma_f32 v[144:145], v[140:141], v[166:167], v[144:145]
	v_add_f32 v146, v144, v145
	ds_read_b128 v[212:215], v5 offset:34048
	ds_read_b128 v[216:219], v5 offset:34304
	ds_read_b128 v[220:223], v5 offset:34560
	ds_read_b128 v[224:227], v5 offset:34816
	ds_read_b32 v228, v9 offset:33792
	ds_read_b128 v[230:233], v5 offset:35328
	v_add_f32_dpp v146, v146, v146 quad_perm:[1,0,3,2] row_mask:0xf bank_mask:0xf bound_ctrl:1
	v_pk_mul_f32 v[246:247], v[138:139], v[246:247]
	v_pk_fma_f32 v[246:247], v[140:141], v[248:249], v[246:247]
	v_add_f32_dpp v146, v146, v146 quad_perm:[2,3,0,1] row_mask:0xf bank_mask:0xf bound_ctrl:1
	s_waitcnt lgkmcnt(12)
	v_pk_mul_f32 v[176:177], v[176:177], v[184:185] op_sel_hi:[1,0]
	v_add_f32_dpp v146, v146, v146 row_half_mirror row_mask:0xf bank_mask:0xf bound_ctrl:1
	v_pk_mul_f32 v[178:179], v[178:179], v[184:185] op_sel_hi:[1,0]
	v_add_f32 v151, v246, v247
	v_add_f32_dpp v146, v146, v146 row_mirror row_mask:0xf bank_mask:0xf bound_ctrl:1
	v_pk_fma_f32 v[176:177], v[146:147], v[168:169], v[176:177] op_sel_hi:[0,1,1] neg_lo:[1,0,0] neg_hi:[1,0,0]
	v_pk_fma_f32 v[178:179], v[146:147], v[170:171], v[178:179] op_sel_hi:[0,1,1] neg_lo:[1,0,0] neg_hi:[1,0,0]
	v_pk_fma_f32 v[138:139], v[138:139], v[172:173], v[176:177]
	v_pk_fma_f32 v[140:141], v[140:141], v[174:175], v[178:179]
	v_pk_mul_f32 v[144:145], v[138:139], v[186:187]
	v_pk_fma_f32 v[144:145], v[140:141], v[188:189], v[144:145]
	v_add_f32 v146, v144, v145
	ds_read_b128 v[234:237], v5 offset:35584
	ds_read_b128 v[238:241], v5 offset:35840
	ds_read_b128 v[242:245], v5 offset:36096
	ds_read_b128 v[246:249], v5 offset:36352
	ds_read_b32 v250, v9 offset:35328
	ds_read_b128 v[164:167], v5 offset:36864
	v_add_f32_dpp v146, v146, v146 quad_perm:[1,0,3,2] row_mask:0xf bank_mask:0xf bound_ctrl:1
	v_pk_mul_f32 v[180:181], v[138:139], v[180:181]
	v_pk_fma_f32 v[180:181], v[140:141], v[182:183], v[180:181]
	v_add_f32_dpp v146, v146, v146 quad_perm:[2,3,0,1] row_mask:0xf bank_mask:0xf bound_ctrl:1
	s_waitcnt lgkmcnt(12)
	v_pk_mul_f32 v[198:199], v[198:199], v[206:207] op_sel_hi:[1,0]
	v_add_f32_dpp v146, v146, v146 row_half_mirror row_mask:0xf bank_mask:0xf bound_ctrl:1
	v_pk_mul_f32 v[200:201], v[200:201], v[206:207] op_sel_hi:[1,0]
	v_add_f32 v152, v180, v181
	v_add_f32_dpp v146, v146, v146 row_mirror row_mask:0xf bank_mask:0xf bound_ctrl:1
	v_pk_fma_f32 v[198:199], v[146:147], v[190:191], v[198:199] op_sel_hi:[0,1,1] neg_lo:[1,0,0] neg_hi:[1,0,0]
	v_pk_fma_f32 v[200:201], v[146:147], v[192:193], v[200:201] op_sel_hi:[0,1,1] neg_lo:[1,0,0] neg_hi:[1,0,0]
	v_pk_fma_f32 v[138:139], v[138:139], v[194:195], v[198:199]
	v_pk_fma_f32 v[140:141], v[140:141], v[196:197], v[200:201]
	v_pk_mul_f32 v[144:145], v[138:139], v[208:209]
	v_pk_fma_f32 v[144:145], v[140:141], v[210:211], v[144:145]
	v_add_f32 v146, v144, v145
	ds_read_b128 v[168:171], v5 offset:37120
	ds_read_b128 v[172:175], v5 offset:37376
	ds_read_b128 v[176:179], v5 offset:37632
	ds_read_b128 v[180:183], v5 offset:37888
	ds_read_b32 v184, v9 offset:36864
	ds_read_b128 v[186:189], v5 offset:38400
	v_add_f32_dpp v146, v146, v146 quad_perm:[1,0,3,2] row_mask:0xf bank_mask:0xf bound_ctrl:1
	v_pk_mul_f32 v[202:203], v[138:139], v[202:203]
	v_pk_fma_f32 v[202:203], v[140:141], v[204:205], v[202:203]
	v_add_f32_dpp v146, v146, v146 quad_perm:[2,3,0,1] row_mask:0xf bank_mask:0xf bound_ctrl:1
	s_waitcnt lgkmcnt(12)
	v_pk_mul_f32 v[220:221], v[220:221], v[228:229] op_sel_hi:[1,0]
	v_add_f32_dpp v146, v146, v146 row_half_mirror row_mask:0xf bank_mask:0xf bound_ctrl:1
	v_pk_mul_f32 v[222:223], v[222:223], v[228:229] op_sel_hi:[1,0]
	v_add_f32 v153, v202, v203
	v_add_f32_dpp v146, v146, v146 row_mirror row_mask:0xf bank_mask:0xf bound_ctrl:1
	v_pk_fma_f32 v[220:221], v[146:147], v[212:213], v[220:221] op_sel_hi:[0,1,1] neg_lo:[1,0,0] neg_hi:[1,0,0]
	v_pk_fma_f32 v[222:223], v[146:147], v[214:215], v[222:223] op_sel_hi:[0,1,1] neg_lo:[1,0,0] neg_hi:[1,0,0]
	v_pk_fma_f32 v[138:139], v[138:139], v[216:217], v[220:221]
	v_pk_fma_f32 v[140:141], v[140:141], v[218:219], v[222:223]
	v_pk_mul_f32 v[144:145], v[138:139], v[230:231]
	v_pk_fma_f32 v[144:145], v[140:141], v[232:233], v[144:145]
	v_add_f32 v146, v144, v145
	ds_read_b128 v[190:193], v5 offset:38656
	ds_read_b128 v[194:197], v5 offset:38912
	ds_read_b128 v[198:201], v5 offset:39168
	ds_read_b128 v[202:205], v5 offset:39424
	ds_read_b32 v206, v9 offset:38400
	ds_read_b128 v[208:211], v5 offset:39936
	v_add_f32_dpp v146, v146, v146 quad_perm:[1,0,3,2] row_mask:0xf bank_mask:0xf bound_ctrl:1
	v_pk_mul_f32 v[224:225], v[138:139], v[224:225]
	v_pk_fma_f32 v[224:225], v[140:141], v[226:227], v[224:225]
	v_add_f32_dpp v146, v146, v146 quad_perm:[2,3,0,1] row_mask:0xf bank_mask:0xf bound_ctrl:1
	s_waitcnt lgkmcnt(12)
	v_pk_mul_f32 v[242:243], v[242:243], v[250:251] op_sel_hi:[1,0]
	v_add_f32_dpp v146, v146, v146 row_half_mirror row_mask:0xf bank_mask:0xf bound_ctrl:1
	v_pk_mul_f32 v[244:245], v[244:245], v[250:251] op_sel_hi:[1,0]
	v_add_f32 v154, v224, v225
	v_add_f32_dpp v146, v146, v146 row_mirror row_mask:0xf bank_mask:0xf bound_ctrl:1
	v_pk_fma_f32 v[242:243], v[146:147], v[234:235], v[242:243] op_sel_hi:[0,1,1] neg_lo:[1,0,0] neg_hi:[1,0,0]
	v_pk_fma_f32 v[244:245], v[146:147], v[236:237], v[244:245] op_sel_hi:[0,1,1] neg_lo:[1,0,0] neg_hi:[1,0,0]
	v_pk_fma_f32 v[138:139], v[138:139], v[238:239], v[242:243]
	v_pk_fma_f32 v[140:141], v[140:141], v[240:241], v[244:245]
	v_pk_mul_f32 v[144:145], v[138:139], v[164:165]
	v_pk_fma_f32 v[144:145], v[140:141], v[166:167], v[144:145]
	v_add_f32 v146, v144, v145
	ds_read_b128 v[212:215], v5 offset:40192
	ds_read_b128 v[216:219], v5 offset:40448
	ds_read_b128 v[220:223], v5 offset:40704
	ds_read_b128 v[224:227], v5 offset:40960
	ds_read_b32 v228, v9 offset:39936
	ds_read_b128 v[230:233], v5 offset:41472
	v_add_f32_dpp v146, v146, v146 quad_perm:[1,0,3,2] row_mask:0xf bank_mask:0xf bound_ctrl:1
	v_pk_mul_f32 v[246:247], v[138:139], v[246:247]
	v_pk_fma_f32 v[246:247], v[140:141], v[248:249], v[246:247]
	v_add_f32_dpp v146, v146, v146 quad_perm:[2,3,0,1] row_mask:0xf bank_mask:0xf bound_ctrl:1
	s_waitcnt lgkmcnt(12)
	v_pk_mul_f32 v[176:177], v[176:177], v[184:185] op_sel_hi:[1,0]
	v_add_f32_dpp v146, v146, v146 row_half_mirror row_mask:0xf bank_mask:0xf bound_ctrl:1
	v_pk_mul_f32 v[178:179], v[178:179], v[184:185] op_sel_hi:[1,0]
	v_add_f32 v155, v246, v247
	v_add_f32_dpp v146, v146, v146 row_mirror row_mask:0xf bank_mask:0xf bound_ctrl:1
	v_pk_fma_f32 v[176:177], v[146:147], v[168:169], v[176:177] op_sel_hi:[0,1,1] neg_lo:[1,0,0] neg_hi:[1,0,0]
	v_pk_fma_f32 v[178:179], v[146:147], v[170:171], v[178:179] op_sel_hi:[0,1,1] neg_lo:[1,0,0] neg_hi:[1,0,0]
	v_pk_fma_f32 v[138:139], v[138:139], v[172:173], v[176:177]
	v_pk_fma_f32 v[140:141], v[140:141], v[174:175], v[178:179]
	v_pk_mul_f32 v[144:145], v[138:139], v[186:187]
	v_pk_fma_f32 v[144:145], v[140:141], v[188:189], v[144:145]
	v_add_f32 v146, v144, v145
	ds_read_b128 v[234:237], v5 offset:41728
	ds_read_b128 v[238:241], v5 offset:41984
	ds_read_b128 v[242:245], v5 offset:42240
	ds_read_b128 v[246:249], v5 offset:42496
	ds_read_b32 v250, v9 offset:41472
	ds_read_b128 v[164:167], v5 offset:43008
	v_add_f32_dpp v146, v146, v146 quad_perm:[1,0,3,2] row_mask:0xf bank_mask:0xf bound_ctrl:1
	v_pk_mul_f32 v[180:181], v[138:139], v[180:181]
	v_pk_fma_f32 v[180:181], v[140:141], v[182:183], v[180:181]
	v_add_f32_dpp v146, v146, v146 quad_perm:[2,3,0,1] row_mask:0xf bank_mask:0xf bound_ctrl:1
	s_waitcnt lgkmcnt(12)
	v_pk_mul_f32 v[198:199], v[198:199], v[206:207] op_sel_hi:[1,0]
	v_add_f32_dpp v146, v146, v146 row_half_mirror row_mask:0xf bank_mask:0xf bound_ctrl:1
	v_pk_mul_f32 v[200:201], v[200:201], v[206:207] op_sel_hi:[1,0]
	v_add_f32 v156, v180, v181
	v_add_f32_dpp v146, v146, v146 row_mirror row_mask:0xf bank_mask:0xf bound_ctrl:1
	v_pk_fma_f32 v[198:199], v[146:147], v[190:191], v[198:199] op_sel_hi:[0,1,1] neg_lo:[1,0,0] neg_hi:[1,0,0]
	v_pk_fma_f32 v[200:201], v[146:147], v[192:193], v[200:201] op_sel_hi:[0,1,1] neg_lo:[1,0,0] neg_hi:[1,0,0]
	v_pk_fma_f32 v[138:139], v[138:139], v[194:195], v[198:199]
	v_pk_fma_f32 v[140:141], v[140:141], v[196:197], v[200:201]
	v_pk_mul_f32 v[144:145], v[138:139], v[208:209]
	v_pk_fma_f32 v[144:145], v[140:141], v[210:211], v[144:145]
	v_add_f32 v146, v144, v145
	ds_read_b128 v[168:171], v5 offset:43264
	ds_read_b128 v[172:175], v5 offset:43520
	ds_read_b128 v[176:179], v5 offset:43776
	ds_read_b128 v[180:183], v5 offset:44032
	ds_read_b32 v184, v9 offset:43008
	ds_read_b128 v[186:189], v5 offset:44544
	v_add_f32_dpp v146, v146, v146 quad_perm:[1,0,3,2] row_mask:0xf bank_mask:0xf bound_ctrl:1
	v_pk_mul_f32 v[202:203], v[138:139], v[202:203]
	v_pk_fma_f32 v[202:203], v[140:141], v[204:205], v[202:203]
	v_add_f32_dpp v146, v146, v146 quad_perm:[2,3,0,1] row_mask:0xf bank_mask:0xf bound_ctrl:1
	s_waitcnt lgkmcnt(12)
	v_pk_mul_f32 v[220:221], v[220:221], v[228:229] op_sel_hi:[1,0]
	v_add_f32_dpp v146, v146, v146 row_half_mirror row_mask:0xf bank_mask:0xf bound_ctrl:1
	v_pk_mul_f32 v[222:223], v[222:223], v[228:229] op_sel_hi:[1,0]
	v_add_f32 v157, v202, v203
	v_add_f32_dpp v146, v146, v146 row_mirror row_mask:0xf bank_mask:0xf bound_ctrl:1
	v_pk_fma_f32 v[220:221], v[146:147], v[212:213], v[220:221] op_sel_hi:[0,1,1] neg_lo:[1,0,0] neg_hi:[1,0,0]
	v_pk_fma_f32 v[222:223], v[146:147], v[214:215], v[222:223] op_sel_hi:[0,1,1] neg_lo:[1,0,0] neg_hi:[1,0,0]
	v_pk_fma_f32 v[138:139], v[138:139], v[216:217], v[220:221]
	v_pk_fma_f32 v[140:141], v[140:141], v[218:219], v[222:223]
	v_pk_mul_f32 v[144:145], v[138:139], v[230:231]
	v_pk_fma_f32 v[144:145], v[140:141], v[232:233], v[144:145]
	v_add_f32 v146, v144, v145
	ds_read_b128 v[190:193], v5 offset:44800
	ds_read_b128 v[194:197], v5 offset:45056
	ds_read_b128 v[198:201], v5 offset:45312
	ds_read_b128 v[202:205], v5 offset:45568
	ds_read_b32 v206, v9 offset:44544
	ds_read_b128 v[208:211], v5 offset:46080
	v_add_f32_dpp v146, v146, v146 quad_perm:[1,0,3,2] row_mask:0xf bank_mask:0xf bound_ctrl:1
	v_pk_mul_f32 v[224:225], v[138:139], v[224:225]
	v_pk_fma_f32 v[224:225], v[140:141], v[226:227], v[224:225]
	v_add_f32_dpp v146, v146, v146 quad_perm:[2,3,0,1] row_mask:0xf bank_mask:0xf bound_ctrl:1
	s_waitcnt lgkmcnt(12)
	v_pk_mul_f32 v[242:243], v[242:243], v[250:251] op_sel_hi:[1,0]
	v_add_f32_dpp v146, v146, v146 row_half_mirror row_mask:0xf bank_mask:0xf bound_ctrl:1
	v_pk_mul_f32 v[244:245], v[244:245], v[250:251] op_sel_hi:[1,0]
	v_add_f32 v158, v224, v225
	v_add_f32_dpp v146, v146, v146 row_mirror row_mask:0xf bank_mask:0xf bound_ctrl:1
	v_pk_fma_f32 v[242:243], v[146:147], v[234:235], v[242:243] op_sel_hi:[0,1,1] neg_lo:[1,0,0] neg_hi:[1,0,0]
	v_pk_fma_f32 v[244:245], v[146:147], v[236:237], v[244:245] op_sel_hi:[0,1,1] neg_lo:[1,0,0] neg_hi:[1,0,0]
	v_pk_fma_f32 v[138:139], v[138:139], v[238:239], v[242:243]
	v_pk_fma_f32 v[140:141], v[140:141], v[240:241], v[244:245]
	v_pk_mul_f32 v[144:145], v[138:139], v[164:165]
	v_pk_fma_f32 v[144:145], v[140:141], v[166:167], v[144:145]
	v_add_f32 v146, v144, v145
	ds_read_b128 v[212:215], v5 offset:46336
	ds_read_b128 v[216:219], v5 offset:46592
	ds_read_b128 v[220:223], v5 offset:46848
	ds_read_b128 v[224:227], v5 offset:47104
	ds_read_b32 v228, v9 offset:46080
	ds_read_b128 v[230:233], v5 offset:47616
	v_add_f32_dpp v146, v146, v146 quad_perm:[1,0,3,2] row_mask:0xf bank_mask:0xf bound_ctrl:1
	v_pk_mul_f32 v[246:247], v[138:139], v[246:247]
	v_pk_fma_f32 v[246:247], v[140:141], v[248:249], v[246:247]
	v_add_f32_dpp v146, v146, v146 quad_perm:[2,3,0,1] row_mask:0xf bank_mask:0xf bound_ctrl:1
	s_waitcnt lgkmcnt(12)
	v_pk_mul_f32 v[176:177], v[176:177], v[184:185] op_sel_hi:[1,0]
	v_add_f32_dpp v146, v146, v146 row_half_mirror row_mask:0xf bank_mask:0xf bound_ctrl:1
	v_pk_mul_f32 v[178:179], v[178:179], v[184:185] op_sel_hi:[1,0]
	v_add_f32 v159, v246, v247
	v_add_f32_dpp v146, v146, v146 row_mirror row_mask:0xf bank_mask:0xf bound_ctrl:1
	v_pk_fma_f32 v[176:177], v[146:147], v[168:169], v[176:177] op_sel_hi:[0,1,1] neg_lo:[1,0,0] neg_hi:[1,0,0]
	v_pk_fma_f32 v[178:179], v[146:147], v[170:171], v[178:179] op_sel_hi:[0,1,1] neg_lo:[1,0,0] neg_hi:[1,0,0]
	v_pk_fma_f32 v[138:139], v[138:139], v[172:173], v[176:177]
	v_pk_fma_f32 v[140:141], v[140:141], v[174:175], v[178:179]
	v_pk_mul_f32 v[144:145], v[138:139], v[186:187]
	v_pk_fma_f32 v[144:145], v[140:141], v[188:189], v[144:145]
	v_add_f32 v146, v144, v145
	ds_read_b128 v[234:237], v5 offset:47872
	ds_read_b128 v[238:241], v5 offset:48128
	ds_read_b128 v[242:245], v5 offset:48384
	ds_read_b128 v[246:249], v5 offset:48640
	ds_read_b32 v250, v9 offset:47616
	v_add_f32_dpp v146, v146, v146 quad_perm:[1,0,3,2] row_mask:0xf bank_mask:0xf bound_ctrl:1
	v_pk_mul_f32 v[180:181], v[138:139], v[180:181]
	v_pk_fma_f32 v[180:181], v[140:141], v[182:183], v[180:181]
	v_add_f32_dpp v146, v146, v146 quad_perm:[2,3,0,1] row_mask:0xf bank_mask:0xf bound_ctrl:1
	s_waitcnt lgkmcnt(11)
	v_pk_mul_f32 v[198:199], v[198:199], v[206:207] op_sel_hi:[1,0]
	v_add_f32_dpp v146, v146, v146 row_half_mirror row_mask:0xf bank_mask:0xf bound_ctrl:1
	v_pk_mul_f32 v[200:201], v[200:201], v[206:207] op_sel_hi:[1,0]
	v_add_f32 v160, v180, v181
	v_add_f32_dpp v146, v146, v146 row_mirror row_mask:0xf bank_mask:0xf bound_ctrl:1
	v_pk_fma_f32 v[198:199], v[146:147], v[190:191], v[198:199] op_sel_hi:[0,1,1] neg_lo:[1,0,0] neg_hi:[1,0,0]
	v_pk_fma_f32 v[200:201], v[146:147], v[192:193], v[200:201] op_sel_hi:[0,1,1] neg_lo:[1,0,0] neg_hi:[1,0,0]
	v_pk_fma_f32 v[138:139], v[138:139], v[194:195], v[198:199]
	v_pk_fma_f32 v[140:141], v[140:141], v[196:197], v[200:201]
	v_pk_mul_f32 v[144:145], v[138:139], v[208:209]
	v_pk_fma_f32 v[144:145], v[140:141], v[210:211], v[144:145]
	v_add_f32 v146, v144, v145
	s_nop 1
	v_add_f32_dpp v146, v146, v146 quad_perm:[1,0,3,2] row_mask:0xf bank_mask:0xf bound_ctrl:1
	v_pk_mul_f32 v[202:203], v[138:139], v[202:203]
	v_pk_fma_f32 v[202:203], v[140:141], v[204:205], v[202:203]
	v_add_f32_dpp v146, v146, v146 quad_perm:[2,3,0,1] row_mask:0xf bank_mask:0xf bound_ctrl:1
	s_waitcnt lgkmcnt(5)
	v_pk_mul_f32 v[220:221], v[220:221], v[228:229] op_sel_hi:[1,0]
	v_add_f32_dpp v146, v146, v146 row_half_mirror row_mask:0xf bank_mask:0xf bound_ctrl:1
	v_pk_mul_f32 v[222:223], v[222:223], v[228:229] op_sel_hi:[1,0]
	v_add_f32 v161, v202, v203
	v_add_f32_dpp v146, v146, v146 row_mirror row_mask:0xf bank_mask:0xf bound_ctrl:1
	v_pk_fma_f32 v[220:221], v[146:147], v[212:213], v[220:221] op_sel_hi:[0,1,1] neg_lo:[1,0,0] neg_hi:[1,0,0]
	v_pk_fma_f32 v[222:223], v[146:147], v[214:215], v[222:223] op_sel_hi:[0,1,1] neg_lo:[1,0,0] neg_hi:[1,0,0]
	v_pk_fma_f32 v[138:139], v[138:139], v[216:217], v[220:221]
	v_pk_fma_f32 v[140:141], v[140:141], v[218:219], v[222:223]
	v_pk_mul_f32 v[144:145], v[138:139], v[230:231]
	v_pk_fma_f32 v[144:145], v[140:141], v[232:233], v[144:145]
	v_add_f32 v146, v144, v145
	s_nop 1
	v_add_f32_dpp v146, v146, v146 quad_perm:[1,0,3,2] row_mask:0xf bank_mask:0xf bound_ctrl:1
	v_pk_mul_f32 v[224:225], v[138:139], v[224:225]
	v_pk_fma_f32 v[224:225], v[140:141], v[226:227], v[224:225]
	v_add_f32_dpp v146, v146, v146 quad_perm:[2,3,0,1] row_mask:0xf bank_mask:0xf bound_ctrl:1
	s_waitcnt lgkmcnt(0)
	v_pk_mul_f32 v[242:243], v[242:243], v[250:251] op_sel_hi:[1,0]
	v_add_f32_dpp v146, v146, v146 row_half_mirror row_mask:0xf bank_mask:0xf bound_ctrl:1
	v_pk_mul_f32 v[244:245], v[244:245], v[250:251] op_sel_hi:[1,0]
	v_add_f32 v162, v224, v225
	v_add_f32_dpp v146, v146, v146 row_mirror row_mask:0xf bank_mask:0xf bound_ctrl:1
	v_pk_fma_f32 v[242:243], v[146:147], v[234:235], v[242:243] op_sel_hi:[0,1,1] neg_lo:[1,0,0] neg_hi:[1,0,0]
	v_pk_fma_f32 v[244:245], v[146:147], v[236:237], v[244:245] op_sel_hi:[0,1,1] neg_lo:[1,0,0] neg_hi:[1,0,0]
	v_pk_fma_f32 v[138:139], v[138:139], v[238:239], v[242:243]
	v_pk_fma_f32 v[140:141], v[140:141], v[240:241], v[244:245]
	v_pk_mul_f32 v[246:247], v[138:139], v[246:247]
	v_pk_fma_f32 v[246:247], v[140:141], v[248:249], v[246:247]
	v_add_f32 v163, v246, v247
	s_nop 0
	v_add_f32_dpp v102, v148, v148 row_mirror row_mask:0xf bank_mask:0x3 bound_ctrl:1
	v_add_f32_dpp v102, v156, v156 row_mirror row_mask:0xf bank_mask:0xc bound_ctrl:1
	v_add_f32_dpp v103, v149, v149 row_mirror row_mask:0xf bank_mask:0x3 bound_ctrl:1
	v_add_f32_dpp v103, v157, v157 row_mirror row_mask:0xf bank_mask:0xc bound_ctrl:1
	v_add_f32_dpp v104, v150, v150 row_mirror row_mask:0xf bank_mask:0x3 bound_ctrl:1
	v_add_f32_dpp v104, v158, v158 row_mirror row_mask:0xf bank_mask:0xc bound_ctrl:1
	v_add_f32_dpp v105, v151, v151 row_mirror row_mask:0xf bank_mask:0x3 bound_ctrl:1
	v_add_f32_dpp v105, v159, v159 row_mirror row_mask:0xf bank_mask:0xc bound_ctrl:1
	v_add_f32_dpp v106, v152, v152 row_mirror row_mask:0xf bank_mask:0x3 bound_ctrl:1
	v_add_f32_dpp v106, v160, v160 row_mirror row_mask:0xf bank_mask:0xc bound_ctrl:1
	v_add_f32_dpp v107, v153, v153 row_mirror row_mask:0xf bank_mask:0x3 bound_ctrl:1
	v_add_f32_dpp v107, v161, v161 row_mirror row_mask:0xf bank_mask:0xc bound_ctrl:1
	v_add_f32_dpp v108, v154, v154 row_mirror row_mask:0xf bank_mask:0x3 bound_ctrl:1
	v_add_f32_dpp v108, v162, v162 row_mirror row_mask:0xf bank_mask:0xc bound_ctrl:1
	v_add_f32_dpp v109, v155, v155 row_mirror row_mask:0xf bank_mask:0x3 bound_ctrl:1
	v_add_f32_dpp v109, v163, v163 row_mirror row_mask:0xf bank_mask:0xc bound_ctrl:1
	v_add_f32_dpp v110, v102, v102 row_half_mirror row_mask:0xf bank_mask:0x5 bound_ctrl:1
	v_add_f32_dpp v110, v106, v106 row_half_mirror row_mask:0xf bank_mask:0xa bound_ctrl:1
	v_add_f32_dpp v111, v103, v103 row_half_mirror row_mask:0xf bank_mask:0x5 bound_ctrl:1
	v_add_f32_dpp v111, v107, v107 row_half_mirror row_mask:0xf bank_mask:0xa bound_ctrl:1
	v_add_f32_dpp v112, v104, v104 row_half_mirror row_mask:0xf bank_mask:0x5 bound_ctrl:1
	v_add_f32_dpp v112, v108, v108 row_half_mirror row_mask:0xf bank_mask:0xa bound_ctrl:1
	v_add_f32_dpp v113, v105, v105 row_half_mirror row_mask:0xf bank_mask:0x5 bound_ctrl:1
	v_add_f32_dpp v113, v109, v109 row_half_mirror row_mask:0xf bank_mask:0xa bound_ctrl:1
	s_mov_b32 vcc_lo, 0xcccccccc
	s_mov_b32 vcc_hi, 0xcccccccc
	v_cndmask_b32 v116, v112, v110, vcc
	v_cndmask_b32 v117, v113, v111, vcc
	v_cndmask_b32 v114, v110, v112, vcc
	v_cndmask_b32 v115, v111, v113, vcc
	v_add_f32_dpp v114, v116, v114 quad_perm:[2,3,0,1] row_mask:0xf bank_mask:0xf bound_ctrl:1
	v_add_f32_dpp v115, v117, v115 quad_perm:[2,3,0,1] row_mask:0xf bank_mask:0xf bound_ctrl:1
	s_mov_b32 vcc_lo, 0xaaaaaaaa
	s_mov_b32 vcc_hi, 0xaaaaaaaa
	v_cndmask_b32 v116, v115, v114, vcc
	v_cndmask_b32 v117, v114, v115, vcc
	s_nop 0
	v_add_f32_dpp v19, v116, v117 quad_perm:[1,0,3,2] row_mask:0xf bank_mask:0xf bound_ctrl:1

; #define SCAN_BAR() asm volatile("s_barrier" ::: "memory")
; __device__ __forceinline__ void scan_unit(const Ctx& C0, const float* scn, int T, int quarter, const float* S0, float* Sout, unsigned char* obase, int mode) {
;     ...
;             if (mode == 0) { *(float*)(obase + (size_t)(k * 32 + q) * UPITCH_B + rl * 4) = osel0; *(float*)(obase + (size_t)(k * 32 + 16 + q) * UPITCH_B + rl * 4) = osel1; }
;             SCAN_BAR();
	v_lshl_add_u64 v[14:15], v[6:7], 0, s[0:1]
	v_add_co_u32_e32 v16, vcc, 0xfc29000, v14
	s_mov_b32 s8, 0xfc7f000
	s_nop 0
	v_addc_co_u32_e32 v17, vcc, 0, v15, vcc
	global_store_dword v[16:17], v18, off offset:768
	v_add_co_u32_e32 v16, vcc, 0xfc54000, v14
	s_add_u32 s0, s0, 0xac000
	s_nop 0
	v_addc_co_u32_e32 v17, vcc, 0, v15, vcc
	global_store_dword v[16:17], v19, off offset:768
	s_barrier
	ds_read_b128 v[164:167], v10 offset:0
	ds_read_b128 v[168:171], v10 offset:256
	ds_read_b128 v[172:175], v10 offset:512
	ds_read_b128 v[176:179], v10 offset:768
	ds_read_b128 v[180:183], v10 offset:1024
	ds_read_b32 v184, v11 offset:0
	ds_read_b128 v[186:189], v10 offset:1536
	ds_read_b128 v[190:193], v10 offset:1792
	ds_read_b128 v[194:197], v10 offset:2048
	ds_read_b128 v[198:201], v10 offset:2304
	ds_read_b128 v[202:205], v10 offset:2560
	ds_read_b32 v206, v11 offset:1536
	ds_read_b128 v[208:211], v10 offset:3072
	s_waitcnt lgkmcnt(12)
	v_pk_mul_f32 v[144:145], v[138:139], v[164:165]
	v_pk_fma_f32 v[144:145], v[140:141], v[166:167], v[144:145]
	v_add_f32 v146, v144, v145
	ds_read_b128 v[212:215], v10 offset:3328
	ds_read_b128 v[216:219], v10 offset:3584
	ds_read_b128 v[220:223], v10 offset:3840
	ds_read_b128 v[224:227], v10 offset:4096
	ds_read_b32 v228, v11 offset:3072
	ds_read_b128 v[230:233], v10 offset:4608
	v_add_f32_dpp v146, v146, v146 quad_perm:[1,0,3,2] row_mask:0xf bank_mask:0xf bound_ctrl:1
	s_nop 0
	s_nop 0
	v_add_f32_dpp v146, v146, v146 quad_perm:[2,3,0,1] row_mask:0xf bank_mask:0xf bound_ctrl:1
	s_waitcnt lgkmcnt(12)
	v_pk_mul_f32 v[176:177], v[176:177], v[184:185] op_sel_hi:[1,0]
	v_add_f32_dpp v146, v146, v146 row_half_mirror row_mask:0xf bank_mask:0xf bound_ctrl:1
	v_pk_mul_f32 v[178:179], v[178:179], v[184:185] op_sel_hi:[1,0]
	s_nop 0
	v_add_f32_dpp v146, v146, v146 row_mirror row_mask:0xf bank_mask:0xf bound_ctrl:1
	v_pk_fma_f32 v[176:177], v[146:147], v[168:169], v[176:177] op_sel_hi:[0,1,1] neg_lo:[1,0,0] neg_hi:[1,0,0]
	v_pk_fma_f32 v[178:179], v[146:147], v[170:171], v[178:179] op_sel_hi:[0,1,1] neg_lo:[1,0,0] neg_hi:[1,0,0]
	v_pk_fma_f32 v[138:139], v[138:139], v[172:173], v[176:177]
	v_pk_fma_f32 v[140:141], v[140:141], v[174:175], v[178:179]
	v_pk_mul_f32 v[144:145], v[138:139], v[186:187]
	v_pk_fma_f32 v[144:145], v[140:141], v[188:189], v[144:145]
	v_add_f32 v146, v144, v145
	ds_read_b128 v[234:237], v10 offset:4864
	ds_read_b128 v[238:241], v10 offset:5120
	ds_read_b128 v[242:245], v10 offset:5376
	ds_read_b128 v[246:249], v10 offset:5632
	ds_read_b32 v250, v11 offset:4608
	ds_read_b128 v[164:167], v10 offset:6144
	v_add_f32_dpp v146, v146, v146 quad_perm:[1,0,3,2] row_mask:0xf bank_mask:0xf bound_ctrl:1
	v_pk_mul_f32 v[180:181], v[138:139], v[180:181]
	v_pk_fma_f32 v[180:181], v[140:141], v[182:183], v[180:181]
	v_add_f32_dpp v146, v146, v146 quad_perm:[2,3,0,1] row_mask:0xf bank_mask:0xf bound_ctrl:1
	s_waitcnt lgkmcnt(12)
	v_pk_mul_f32 v[198:199], v[198:199], v[206:207] op_sel_hi:[1,0]
	v_add_f32_dpp v146, v146, v146 row_half_mirror row_mask:0xf bank_mask:0xf bound_ctrl:1
	v_pk_mul_f32 v[200:201], v[200:201], v[206:207] op_sel_hi:[1,0]
	v_add_f32 v148, v180, v181
	v_add_f32_dpp v146, v146, v146 row_mirror row_mask:0xf bank_mask:0xf bound_ctrl:1
	v_pk_fma_f32 v[198:199], v[146:147], v[190:191], v[198:199] op_sel_hi:[0,1,1] neg_lo:[1,0,0] neg_hi:[1,0,0]
	v_pk_fma_f32 v[200:201], v[146:147], v[192:193], v[200:201] op_sel_hi:[0,1,1] neg_lo:[1,0,0] neg_hi:[1,0,0]
	v_pk_fma_f32 v[138:139], v[138:139], v[194:195], v[198:199]
	v_pk_fma_f32 v[140:141], v[140:141], v[196:197], v[200:201]
	v_pk_mul_f32 v[144:145], v[138:139], v[208:209]
	v_pk_fma_f32 v[144:145], v[140:141], v[210:211], v[144:145]
	v_add_f32 v146, v144, v145
	ds_read_b128 v[168:171], v10 offset:6400
	ds_read_b128 v[172:175], v10 offset:6656
	ds_read_b128 v[176:179], v10 offset:6912
	ds_read_b128 v[180:183], v10 offset:7168
	ds_read_b32 v184, v11 offset:6144
	ds_read_b128 v[186:189], v10 offset:7680
	v_add_f32_dpp v146, v146, v146 quad_perm:[1,0,3,2] row_mask:0xf bank_mask:0xf bound_ctrl:1
	v_pk_mul_f32 v[202:203], v[138:139], v[202:203]
	v_pk_fma_f32 v[202:203], v[140:141], v[204:205], v[202:203]
	v_add_f32_dpp v146, v146, v146 quad_perm:[2,3,0,1] row_mask:0xf bank_mask:0xf bound_ctrl:1
	s_waitcnt lgkmcnt(12)
	v_pk_mul_f32 v[220:221], v[220:221], v[228:229] op_sel_hi:[1,0]
	v_add_f32_dpp v146, v146, v146 row_half_mirror row_mask:0xf bank_mask:0xf bound_ctrl:1
	v_pk_mul_f32 v[222:223], v[222:223], v[228:229] op_sel_hi:[1,0]
	v_add_f32 v149, v202, v203
	v_add_f32_dpp v146, v146, v146 row_mirror row_mask:0xf bank_mask:0xf bound_ctrl:1
	v_pk_fma_f32 v[220:221], v[146:147], v[212:213], v[220:221] op_sel_hi:[0,1,1] neg_lo:[1,0,0] neg_hi:[1,0,0]
	v_pk_fma_f32 v[222:223], v[146:147], v[214:215], v[222:223] op_sel_hi:[0,1,1] neg_lo:[1,0,0] neg_hi:[1,0,0]
	v_pk_fma_f32 v[138:139], v[138:139], v[216:217], v[220:221]
	v_pk_fma_f32 v[140:141], v[140:141], v[218:219], v[222:223]
	v_pk_mul_f32 v[144:145], v[138:139], v[230:231]
	v_pk_fma_f32 v[144:145], v[140:141], v[232:233], v[144:145]
	v_add_f32 v146, v144, v145
	ds_read_b128 v[190:193], v10 offset:7936
	ds_read_b128 v[194:197], v10 offset:8192
	ds_read_b128 v[198:201], v10 offset:8448
	ds_read_b128 v[202:205], v10 offset:8704
	ds_read_b32 v206, v11 offset:7680
	ds_read_b128 v[208:211], v10 offset:9216
	v_add_f32_dpp v146, v146, v146 quad_perm:[1,0,3,2] row_mask:0xf bank_mask:0xf bound_ctrl:1
	v_pk_mul_f32 v[224:225], v[138:139], v[224:225]
	v_pk_fma_f32 v[224:225], v[140:141], v[226:227], v[224:225]
	v_add_f32_dpp v146, v146, v146 quad_perm:[2,3,0,1] row_mask:0xf bank_mask:0xf bound_ctrl:1
	s_waitcnt lgkmcnt(12)
	v_pk_mul_f32 v[242:243], v[242:243], v[250:251] op_sel_hi:[1,0]
	v_add_f32_dpp v146, v146, v146 row_half_mirror row_mask:0xf bank_mask:0xf bound_ctrl:1
	v_pk_mul_f32 v[244:245], v[244:245], v[250:251] op_sel_hi:[1,0]
	v_add_f32 v150, v224, v225
	v_add_f32_dpp v146, v146, v146 row_mirror row_mask:0xf bank_mask:0xf bound_ctrl:1
	v_pk_fma_f32 v[242:243], v[146:147], v[234:235], v[242:243] op_sel_hi:[0,1,1] neg_lo:[1,0,0] neg_hi:[1,0,0]
	v_pk_fma_f32 v[244:245], v[146:147], v[236:237], v[244:245] op_sel_hi:[0,1,1] neg_lo:[1,0,0] neg_hi:[1,0,0]
	v_pk_fma_f32 v[138:139], v[138:139], v[238:239], v[242:243]
	v_pk_fma_f32 v[140:141], v[140:141], v[240:241], v[244:245]
	v_pk_mul_f32 v[144:145], v[138:139], v[164:165]
	v_pk_fma_f32 v[144:145], v[140:141], v[166:167], v[144:145]
	v_add_f32 v146, v144, v145
	ds_read_b128 v[212:215], v10 offset:9472
	ds_read_b128 v[216:219], v10 offset:9728
	ds_read_b128 v[220:223], v10 offset:9984
	ds_read_b128 v[224:227], v10 offset:10240
	ds_read_b32 v228, v11 offset:9216
	ds_read_b128 v[230:233], v10 offset:10752
	v_add_f32_dpp v146, v146, v146 quad_perm:[1,0,3,2] row_mask:0xf bank_mask:0xf bound_ctrl:1
	v_pk_mul_f32 v[246:247], v[138:139], v[246:247]
	v_pk_fma_f32 v[246:247], v[140:141], v[248:249], v[246:247]
	v_add_f32_dpp v146, v146, v146 quad_perm:[2,3,0,1] row_mask:0xf bank_mask:0xf bound_ctrl:1
	s_waitcnt lgkmcnt(12)
	v_pk_mul_f32 v[176:177], v[176:177], v[184:185] op_sel_hi:[1,0]
	v_add_f32_dpp v146, v146, v146 row_half_mirror row_mask:0xf bank_mask:0xf bound_ctrl:1
	v_pk_mul_f32 v[178:179], v[178:179], v[184:185] op_sel_hi:[1,0]
	v_add_f32 v151, v246, v247
	v_add_f32_dpp v146, v146, v146 row_mirror row_mask:0xf bank_mask:0xf bound_ctrl:1
	v_pk_fma_f32 v[176:177], v[146:147], v[168:169], v[176:177] op_sel_hi:[0,1,1] neg_lo:[1,0,0] neg_hi:[1,0,0]
	v_pk_fma_f32 v[178:179], v[146:147], v[170:171], v[178:179] op_sel_hi:[0,1,1] neg_lo:[1,0,0] neg_hi:[1,0,0]
	v_pk_fma_f32 v[138:139], v[138:139], v[172:173], v[176:177]
	v_pk_fma_f32 v[140:141], v[140:141], v[174:175], v[178:179]
	v_pk_mul_f32 v[144:145], v[138:139], v[186:187]
	v_pk_fma_f32 v[144:145], v[140:141], v[188:189], v[144:145]
	v_add_f32 v146, v144, v145
	ds_read_b128 v[234:237], v10 offset:11008
	ds_read_b128 v[238:241], v10 offset:11264
	ds_read_b128 v[242:245], v10 offset:11520
	ds_read_b128 v[246:249], v10 offset:11776
	ds_read_b32 v250, v11 offset:10752
	ds_read_b128 v[164:167], v10 offset:12288
	v_add_f32_dpp v146, v146, v146 quad_perm:[1,0,3,2] row_mask:0xf bank_mask:0xf bound_ctrl:1
	v_pk_mul_f32 v[180:181], v[138:139], v[180:181]
	v_pk_fma_f32 v[180:181], v[140:141], v[182:183], v[180:181]
	v_add_f32_dpp v146, v146, v146 quad_perm:[2,3,0,1] row_mask:0xf bank_mask:0xf bound_ctrl:1
	s_waitcnt lgkmcnt(12)
	v_pk_mul_f32 v[198:199], v[198:199], v[206:207] op_sel_hi:[1,0]
	v_add_f32_dpp v146, v146, v146 row_half_mirror row_mask:0xf bank_mask:0xf bound_ctrl:1
	v_pk_mul_f32 v[200:201], v[200:201], v[206:207] op_sel_hi:[1,0]
	v_add_f32 v152, v180, v181
	v_add_f32_dpp v146, v146, v146 row_mirror row_mask:0xf bank_mask:0xf bound_ctrl:1
	v_pk_fma_f32 v[198:199], v[146:147], v[190:191], v[198:199] op_sel_hi:[0,1,1] neg_lo:[1,0,0] neg_hi:[1,0,0]
	v_pk_fma_f32 v[200:201], v[146:147], v[192:193], v[200:201] op_sel_hi:[0,1,1] neg_lo:[1,0,0] neg_hi:[1,0,0]
	v_pk_fma_f32 v[138:139], v[138:139], v[194:195], v[198:199]
	v_pk_fma_f32 v[140:141], v[140:141], v[196:197], v[200:201]
	v_pk_mul_f32 v[144:145], v[138:139], v[208:209]
	v_pk_fma_f32 v[144:145], v[140:141], v[210:211], v[144:145]
	v_add_f32 v146, v144, v145
	ds_read_b128 v[168:171], v10 offset:12544
	ds_read_b128 v[172:175], v10 offset:12800
	ds_read_b128 v[176:179], v10 offset:13056
	ds_read_b128 v[180:183], v10 offset:13312
	ds_read_b32 v184, v11 offset:12288
	ds_read_b128 v[186:189], v10 offset:13824
	v_add_f32_dpp v146, v146, v146 quad_perm:[1,0,3,2] row_mask:0xf bank_mask:0xf bound_ctrl:1
	v_pk_mul_f32 v[202:203], v[138:139], v[202:203]
	v_pk_fma_f32 v[202:203], v[140:141], v[204:205], v[202:203]
	v_add_f32_dpp v146, v146, v146 quad_perm:[2,3,0,1] row_mask:0xf bank_mask:0xf bound_ctrl:1
	s_waitcnt lgkmcnt(12)
	v_pk_mul_f32 v[220:221], v[220:221], v[228:229] op_sel_hi:[1,0]
	v_add_f32_dpp v146, v146, v146 row_half_mirror row_mask:0xf bank_mask:0xf bound_ctrl:1
	v_pk_mul_f32 v[222:223], v[222:223], v[228:229] op_sel_hi:[1,0]
	v_add_f32 v153, v202, v203
	v_add_f32_dpp v146, v146, v146 row_mirror row_mask:0xf bank_mask:0xf bound_ctrl:1
	v_pk_fma_f32 v[220:221], v[146:147], v[212:213], v[220:221] op_sel_hi:[0,1,1] neg_lo:[1,0,0] neg_hi:[1,0,0]
	v_pk_fma_f32 v[222:223], v[146:147], v[214:215], v[222:223] op_sel_hi:[0,1,1] neg_lo:[1,0,0] neg_hi:[1,0,0]
	v_pk_fma_f32 v[138:139], v[138:139], v[216:217], v[220:221]
	v_pk_fma_f32 v[140:141], v[140:141], v[218:219], v[222:223]
	v_pk_mul_f32 v[144:145], v[138:139], v[230:231]
	v_pk_fma_f32 v[144:145], v[140:141], v[232:233], v[144:145]
	v_add_f32 v146, v144, v145
	ds_read_b128 v[190:193], v10 offset:14080
	ds_read_b128 v[194:197], v10 offset:14336
	ds_read_b128 v[198:201], v10 offset:14592
	ds_read_b128 v[202:205], v10 offset:14848
	ds_read_b32 v206, v11 offset:13824
	ds_read_b128 v[208:211], v10 offset:15360
	v_add_f32_dpp v146, v146, v146 quad_perm:[1,0,3,2] row_mask:0xf bank_mask:0xf bound_ctrl:1
	v_pk_mul_f32 v[224:225], v[138:139], v[224:225]
	v_pk_fma_f32 v[224:225], v[140:141], v[226:227], v[224:225]
	v_add_f32_dpp v146, v146, v146 quad_perm:[2,3,0,1] row_mask:0xf bank_mask:0xf bound_ctrl:1
	s_waitcnt lgkmcnt(12)
	v_pk_mul_f32 v[242:243], v[242:243], v[250:251] op_sel_hi:[1,0]
	v_add_f32_dpp v146, v146, v146 row_half_mirror row_mask:0xf bank_mask:0xf bound_ctrl:1
	v_pk_mul_f32 v[244:245], v[244:245], v[250:251] op_sel_hi:[1,0]
	v_add_f32 v154, v224, v225
	v_add_f32_dpp v146, v146, v146 row_mirror row_mask:0xf bank_mask:0xf bound_ctrl:1
	v_pk_fma_f32 v[242:243], v[146:147], v[234:235], v[242:243] op_sel_hi:[0,1,1] neg_lo:[1,0,0] neg_hi:[1,0,0]
	v_pk_fma_f32 v[244:245], v[146:147], v[236:237], v[244:245] op_sel_hi:[0,1,1] neg_lo:[1,0,0] neg_hi:[1,0,0]
	v_pk_fma_f32 v[138:139], v[138:139], v[238:239], v[242:243]
	v_pk_fma_f32 v[140:141], v[140:141], v[240:241], v[244:245]
	v_pk_mul_f32 v[144:145], v[138:139], v[164:165]
	v_pk_fma_f32 v[144:145], v[140:141], v[166:167], v[144:145]
	v_add_f32 v146, v144, v145
	ds_read_b128 v[212:215], v10 offset:15616
	ds_read_b128 v[216:219], v10 offset:15872
	ds_read_b128 v[220:223], v10 offset:16128
	ds_read_b128 v[224:227], v10 offset:16384
	ds_read_b32 v228, v11 offset:15360
	ds_read_b128 v[230:233], v10 offset:16896
	v_add_f32_dpp v146, v146, v146 quad_perm:[1,0,3,2] row_mask:0xf bank_mask:0xf bound_ctrl:1
	v_pk_mul_f32 v[246:247], v[138:139], v[246:247]
	v_pk_fma_f32 v[246:247], v[140:141], v[248:249], v[246:247]
	v_add_f32_dpp v146, v146, v146 quad_perm:[2,3,0,1] row_mask:0xf bank_mask:0xf bound_ctrl:1
	s_waitcnt lgkmcnt(12)
	v_pk_mul_f32 v[176:177], v[176:177], v[184:185] op_sel_hi:[1,0]
	v_add_f32_dpp v146, v146, v146 row_half_mirror row_mask:0xf bank_mask:0xf bound_ctrl:1
	v_pk_mul_f32 v[178:179], v[178:179], v[184:185] op_sel_hi:[1,0]
	v_add_f32 v155, v246, v247
	v_add_f32_dpp v146, v146, v146 row_mirror row_mask:0xf bank_mask:0xf bound_ctrl:1
	v_pk_fma_f32 v[176:177], v[146:147], v[168:169], v[176:177] op_sel_hi:[0,1,1] neg_lo:[1,0,0] neg_hi:[1,0,0]
	v_pk_fma_f32 v[178:179], v[146:147], v[170:171], v[178:179] op_sel_hi:[0,1,1] neg_lo:[1,0,0] neg_hi:[1,0,0]
	v_pk_fma_f32 v[138:139], v[138:139], v[172:173], v[176:177]
	v_pk_fma_f32 v[140:141], v[140:141], v[174:175], v[178:179]
	v_pk_mul_f32 v[144:145], v[138:139], v[186:187]
	v_pk_fma_f32 v[144:145], v[140:141], v[188:189], v[144:145]
	v_add_f32 v146, v144, v145
	ds_read_b128 v[234:237], v10 offset:17152
	ds_read_b128 v[238:241], v10 offset:17408
	ds_read_b128 v[242:245], v10 offset:17664
	ds_read_b128 v[246:249], v10 offset:17920
	ds_read_b32 v250, v11 offset:16896
	ds_read_b128 v[164:167], v10 offset:18432
	v_add_f32_dpp v146, v146, v146 quad_perm:[1,0,3,2] row_mask:0xf bank_mask:0xf bound_ctrl:1
	v_pk_mul_f32 v[180:181], v[138:139], v[180:181]
	v_pk_fma_f32 v[180:181], v[140:141], v[182:183], v[180:181]
	v_add_f32_dpp v146, v146, v146 quad_perm:[2,3,0,1] row_mask:0xf bank_mask:0xf bound_ctrl:1
	s_waitcnt lgkmcnt(12)
	v_pk_mul_f32 v[198:199], v[198:199], v[206:207] op_sel_hi:[1,0]
	v_add_f32_dpp v146, v146, v146 row_half_mirror row_mask:0xf bank_mask:0xf bound_ctrl:1
	v_pk_mul_f32 v[200:201], v[200:201], v[206:207] op_sel_hi:[1,0]
	v_add_f32 v156, v180, v181
	v_add_f32_dpp v146, v146, v146 row_mirror row_mask:0xf bank_mask:0xf bound_ctrl:1
	v_pk_fma_f32 v[198:199], v[146:147], v[190:191], v[198:199] op_sel_hi:[0,1,1] neg_lo:[1,0,0] neg_hi:[1,0,0]
	v_pk_fma_f32 v[200:201], v[146:147], v[192:193], v[200:201] op_sel_hi:[0,1,1] neg_lo:[1,0,0] neg_hi:[1,0,0]
	v_pk_fma_f32 v[138:139], v[138:139], v[194:195], v[198:199]
	v_pk_fma_f32 v[140:141], v[140:141], v[196:197], v[200:201]
	v_pk_mul_f32 v[144:145], v[138:139], v[208:209]
	v_pk_fma_f32 v[144:145], v[140:141], v[210:211], v[144:145]
	v_add_f32 v146, v144, v145
	ds_read_b128 v[168:171], v10 offset:18688
	ds_read_b128 v[172:175], v10 offset:18944
	ds_read_b128 v[176:179], v10 offset:19200
	ds_read_b128 v[180:183], v10 offset:19456
	ds_read_b32 v184, v11 offset:18432
	ds_read_b128 v[186:189], v10 offset:19968
	v_add_f32_dpp v146, v146, v146 quad_perm:[1,0,3,2] row_mask:0xf bank_mask:0xf bound_ctrl:1
	v_pk_mul_f32 v[202:203], v[138:139], v[202:203]
	v_pk_fma_f32 v[202:203], v[140:141], v[204:205], v[202:203]
	v_add_f32_dpp v146, v146, v146 quad_perm:[2,3,0,1] row_mask:0xf bank_mask:0xf bound_ctrl:1
	s_waitcnt lgkmcnt(12)
	v_pk_mul_f32 v[220:221], v[220:221], v[228:229] op_sel_hi:[1,0]
	v_add_f32_dpp v146, v146, v146 row_half_mirror row_mask:0xf bank_mask:0xf bound_ctrl:1
	v_pk_mul_f32 v[222:223], v[222:223], v[228:229] op_sel_hi:[1,0]
	v_add_f32 v157, v202, v203
	v_add_f32_dpp v146, v146, v146 row_mirror row_mask:0xf bank_mask:0xf bound_ctrl:1
	v_pk_fma_f32 v[220:221], v[146:147], v[212:213], v[220:221] op_sel_hi:[0,1,1] neg_lo:[1,0,0] neg_hi:[1,0,0]
	v_pk_fma_f32 v[222:223], v[146:147], v[214:215], v[222:223] op_sel_hi:[0,1,1] neg_lo:[1,0,0] neg_hi:[1,0,0]
	v_pk_fma_f32 v[138:139], v[138:139], v[216:217], v[220:221]
	v_pk_fma_f32 v[140:141], v[140:141], v[218:219], v[222:223]
	v_pk_mul_f32 v[144:145], v[138:139], v[230:231]
	v_pk_fma_f32 v[144:145], v[140:141], v[232:233], v[144:145]
	v_add_f32 v146, v144, v145
	ds_read_b128 v[190:193], v10 offset:20224
	ds_read_b128 v[194:197], v10 offset:20480
	ds_read_b128 v[198:201], v10 offset:20736
	ds_read_b128 v[202:205], v10 offset:20992
	ds_read_b32 v206, v11 offset:19968
	ds_read_b128 v[208:211], v10 offset:21504
	v_add_f32_dpp v146, v146, v146 quad_perm:[1,0,3,2] row_mask:0xf bank_mask:0xf bound_ctrl:1
	v_pk_mul_f32 v[224:225], v[138:139], v[224:225]
	v_pk_fma_f32 v[224:225], v[140:141], v[226:227], v[224:225]
	v_add_f32_dpp v146, v146, v146 quad_perm:[2,3,0,1] row_mask:0xf bank_mask:0xf bound_ctrl:1
	s_waitcnt lgkmcnt(12)
	v_pk_mul_f32 v[242:243], v[242:243], v[250:251] op_sel_hi:[1,0]
	v_add_f32_dpp v146, v146, v146 row_half_mirror row_mask:0xf bank_mask:0xf bound_ctrl:1
	v_pk_mul_f32 v[244:245], v[244:245], v[250:251] op_sel_hi:[1,0]
	v_add_f32 v158, v224, v225
	v_add_f32_dpp v146, v146, v146 row_mirror row_mask:0xf bank_mask:0xf bound_ctrl:1
	v_pk_fma_f32 v[242:243], v[146:147], v[234:235], v[242:243] op_sel_hi:[0,1,1] neg_lo:[1,0,0] neg_hi:[1,0,0]
	v_pk_fma_f32 v[244:245], v[146:147], v[236:237], v[244:245] op_sel_hi:[0,1,1] neg_lo:[1,0,0] neg_hi:[1,0,0]
	v_pk_fma_f32 v[138:139], v[138:139], v[238:239], v[242:243]
	v_pk_fma_f32 v[140:141], v[140:141], v[240:241], v[244:245]
	v_pk_mul_f32 v[144:145], v[138:139], v[164:165]
	v_pk_fma_f32 v[144:145], v[140:141], v[166:167], v[144:145]
	v_add_f32 v146, v144, v145
	ds_read_b128 v[212:215], v10 offset:21760
	ds_read_b128 v[216:219], v10 offset:22016
	ds_read_b128 v[220:223], v10 offset:22272
	ds_read_b128 v[224:227], v10 offset:22528
	ds_read_b32 v228, v11 offset:21504
	ds_read_b128 v[230:233], v10 offset:23040
	v_add_f32_dpp v146, v146, v146 quad_perm:[1,0,3,2] row_mask:0xf bank_mask:0xf bound_ctrl:1
	v_pk_mul_f32 v[246:247], v[138:139], v[246:247]
	v_pk_fma_f32 v[246:247], v[140:141], v[248:249], v[246:247]
	v_add_f32_dpp v146, v146, v146 quad_perm:[2,3,0,1] row_mask:0xf bank_mask:0xf bound_ctrl:1
	s_waitcnt lgkmcnt(12)
	v_pk_mul_f32 v[176:177], v[176:177], v[184:185] op_sel_hi:[1,0]
	v_add_f32_dpp v146, v146, v146 row_half_mirror row_mask:0xf bank_mask:0xf bound_ctrl:1
	v_pk_mul_f32 v[178:179], v[178:179], v[184:185] op_sel_hi:[1,0]
	v_add_f32 v159, v246, v247
	v_add_f32_dpp v146, v146, v146 row_mirror row_mask:0xf bank_mask:0xf bound_ctrl:1
	v_pk_fma_f32 v[176:177], v[146:147], v[168:169], v[176:177] op_sel_hi:[0,1,1] neg_lo:[1,0,0] neg_hi:[1,0,0]
	v_pk_fma_f32 v[178:179], v[146:147], v[170:171], v[178:179] op_sel_hi:[0,1,1] neg_lo:[1,0,0] neg_hi:[1,0,0]
	v_pk_fma_f32 v[138:139], v[138:139], v[172:173], v[176:177]
	v_pk_fma_f32 v[140:141], v[140:141], v[174:175], v[178:179]
	v_pk_mul_f32 v[144:145], v[138:139], v[186:187]
	v_pk_fma_f32 v[144:145], v[140:141], v[188:189], v[144:145]
	v_add_f32 v146, v144, v145
	ds_read_b128 v[234:237], v10 offset:23296
	ds_read_b128 v[238:241], v10 offset:23552
	ds_read_b128 v[242:245], v10 offset:23808
	ds_read_b128 v[246:249], v10 offset:24064
	ds_read_b32 v250, v11 offset:23040
	ds_read_b128 v[164:167], v10 offset:24576
	v_add_f32_dpp v146, v146, v146 quad_perm:[1,0,3,2] row_mask:0xf bank_mask:0xf bound_ctrl:1
	v_pk_mul_f32 v[180:181], v[138:139], v[180:181]
	v_pk_fma_f32 v[180:181], v[140:141], v[182:183], v[180:181]
	v_add_f32_dpp v146, v146, v146 quad_perm:[2,3,0,1] row_mask:0xf bank_mask:0xf bound_ctrl:1
	s_waitcnt lgkmcnt(12)
	v_pk_mul_f32 v[198:199], v[198:199], v[206:207] op_sel_hi:[1,0]
	v_add_f32_dpp v146, v146, v146 row_half_mirror row_mask:0xf bank_mask:0xf bound_ctrl:1
	v_pk_mul_f32 v[200:201], v[200:201], v[206:207] op_sel_hi:[1,0]
	v_add_f32 v160, v180, v181
	v_add_f32_dpp v146, v146, v146 row_mirror row_mask:0xf bank_mask:0xf bound_ctrl:1
	v_pk_fma_f32 v[198:199], v[146:147], v[190:191], v[198:199] op_sel_hi:[0,1,1] neg_lo:[1,0,0] neg_hi:[1,0,0]
	v_pk_fma_f32 v[200:201], v[146:147], v[192:193], v[200:201] op_sel_hi:[0,1,1] neg_lo:[1,0,0] neg_hi:[1,0,0]
	v_pk_fma_f32 v[138:139], v[138:139], v[194:195], v[198:199]
	v_pk_fma_f32 v[140:141], v[140:141], v[196:197], v[200:201]
	v_pk_mul_f32 v[144:145], v[138:139], v[208:209]
	v_pk_fma_f32 v[144:145], v[140:141], v[210:211], v[144:145]
	v_add_f32 v146, v144, v145
	ds_read_b128 v[168:171], v10 offset:24832
	ds_read_b128 v[172:175], v10 offset:25088
	ds_read_b128 v[176:179], v10 offset:25344
	ds_read_b128 v[180:183], v10 offset:25600
	ds_read_b32 v184, v11 offset:24576
	ds_read_b128 v[186:189], v10 offset:26112
	v_add_f32_dpp v146, v146, v146 quad_perm:[1,0,3,2] row_mask:0xf bank_mask:0xf bound_ctrl:1
	v_pk_mul_f32 v[202:203], v[138:139], v[202:203]
	v_pk_fma_f32 v[202:203], v[140:141], v[204:205], v[202:203]
	v_add_f32_dpp v146, v146, v146 quad_perm:[2,3,0,1] row_mask:0xf bank_mask:0xf bound_ctrl:1
	s_waitcnt lgkmcnt(12)
	v_pk_mul_f32 v[220:221], v[220:221], v[228:229] op_sel_hi:[1,0]
	v_add_f32_dpp v146, v146, v146 row_half_mirror row_mask:0xf bank_mask:0xf bound_ctrl:1
	v_pk_mul_f32 v[222:223], v[222:223], v[228:229] op_sel_hi:[1,0]
	v_add_f32 v161, v202, v203
	v_add_f32_dpp v146, v146, v146 row_mirror row_mask:0xf bank_mask:0xf bound_ctrl:1
	v_pk_fma_f32 v[220:221], v[146:147], v[212:213], v[220:221] op_sel_hi:[0,1,1] neg_lo:[1,0,0] neg_hi:[1,0,0]
	v_pk_fma_f32 v[222:223], v[146:147], v[214:215], v[222:223] op_sel_hi:[0,1,1] neg_lo:[1,0,0] neg_hi:[1,0,0]
	v_pk_fma_f32 v[138:139], v[138:139], v[216:217], v[220:221]
	v_pk_fma_f32 v[140:141], v[140:141], v[218:219], v[222:223]
	v_pk_mul_f32 v[144:145], v[138:139], v[230:231]
	v_pk_fma_f32 v[144:145], v[140:141], v[232:233], v[144:145]
	v_add_f32 v146, v144, v145
	ds_read_b128 v[190:193], v10 offset:26368
	ds_read_b128 v[194:197], v10 offset:26624
	ds_read_b128 v[198:201], v10 offset:26880
	ds_read_b128 v[202:205], v10 offset:27136
	ds_read_b32 v206, v11 offset:26112
	ds_read_b128 v[208:211], v10 offset:27648
	v_add_f32_dpp v146, v146, v146 quad_perm:[1,0,3,2] row_mask:0xf bank_mask:0xf bound_ctrl:1
	v_pk_mul_f32 v[224:225], v[138:139], v[224:225]
	v_pk_fma_f32 v[224:225], v[140:141], v[226:227], v[224:225]
	v_add_f32_dpp v146, v146, v146 quad_perm:[2,3,0,1] row_mask:0xf bank_mask:0xf bound_ctrl:1
	s_waitcnt lgkmcnt(12)
	v_pk_mul_f32 v[242:243], v[242:243], v[250:251] op_sel_hi:[1,0]
	v_add_f32_dpp v146, v146, v146 row_half_mirror row_mask:0xf bank_mask:0xf bound_ctrl:1
	v_pk_mul_f32 v[244:245], v[244:245], v[250:251] op_sel_hi:[1,0]
	v_add_f32 v162, v224, v225
	v_add_f32_dpp v146, v146, v146 row_mirror row_mask:0xf bank_mask:0xf bound_ctrl:1
	v_pk_fma_f32 v[242:243], v[146:147], v[234:235], v[242:243] op_sel_hi:[0,1,1] neg_lo:[1,0,0] neg_hi:[1,0,0]
	v_pk_fma_f32 v[244:245], v[146:147], v[236:237], v[244:245] op_sel_hi:[0,1,1] neg_lo:[1,0,0] neg_hi:[1,0,0]
	v_pk_fma_f32 v[138:139], v[138:139], v[238:239], v[242:243]
	v_pk_fma_f32 v[140:141], v[140:141], v[240:241], v[244:245]
	v_pk_mul_f32 v[144:145], v[138:139], v[164:165]
	v_pk_fma_f32 v[144:145], v[140:141], v[166:167], v[144:145]
	v_add_f32 v146, v144, v145
	ds_read_b128 v[212:215], v10 offset:27904
	ds_read_b128 v[216:219], v10 offset:28160
	ds_read_b128 v[220:223], v10 offset:28416
	ds_read_b128 v[224:227], v10 offset:28672
	ds_read_b32 v228, v11 offset:27648
	ds_read_b128 v[230:233], v10 offset:29184
	v_add_f32_dpp v146, v146, v146 quad_perm:[1,0,3,2] row_mask:0xf bank_mask:0xf bound_ctrl:1
	v_pk_mul_f32 v[246:247], v[138:139], v[246:247]
	v_pk_fma_f32 v[246:247], v[140:141], v[248:249], v[246:247]
	v_add_f32_dpp v146, v146, v146 quad_perm:[2,3,0,1] row_mask:0xf bank_mask:0xf bound_ctrl:1
	s_waitcnt lgkmcnt(12)
	v_pk_mul_f32 v[176:177], v[176:177], v[184:185] op_sel_hi:[1,0]
	v_add_f32_dpp v146, v146, v146 row_half_mirror row_mask:0xf bank_mask:0xf bound_ctrl:1
	v_pk_mul_f32 v[178:179], v[178:179], v[184:185] op_sel_hi:[1,0]
	v_add_f32 v163, v246, v247
	v_add_f32_dpp v146, v146, v146 row_mirror row_mask:0xf bank_mask:0xf bound_ctrl:1
	v_pk_fma_f32 v[176:177], v[146:147], v[168:169], v[176:177] op_sel_hi:[0,1,1] neg_lo:[1,0,0] neg_hi:[1,0,0]
	v_pk_fma_f32 v[178:179], v[146:147], v[170:171], v[178:179] op_sel_hi:[0,1,1] neg_lo:[1,0,0] neg_hi:[1,0,0]
	v_pk_fma_f32 v[138:139], v[138:139], v[172:173], v[176:177]
	v_pk_fma_f32 v[140:141], v[140:141], v[174:175], v[178:179]
	v_pk_mul_f32 v[144:145], v[138:139], v[186:187]
	v_pk_fma_f32 v[144:145], v[140:141], v[188:189], v[144:145]
	v_add_f32 v146, v144, v145
	ds_read_b128 v[234:237], v10 offset:29440
	ds_read_b128 v[238:241], v10 offset:29696
	ds_read_b128 v[242:245], v10 offset:29952
	ds_read_b128 v[246:249], v10 offset:30208
	ds_read_b32 v250, v11 offset:29184
	ds_read_b128 v[164:167], v10 offset:30720
	v_add_f32_dpp v102, v148, v148 row_mirror row_mask:0xf bank_mask:0x3 bound_ctrl:1
	v_add_f32_dpp v102, v156, v156 row_mirror row_mask:0xf bank_mask:0xc bound_ctrl:1
	v_add_f32_dpp v103, v149, v149 row_mirror row_mask:0xf bank_mask:0x3 bound_ctrl:1
	v_add_f32_dpp v103, v157, v157 row_mirror row_mask:0xf bank_mask:0xc bound_ctrl:1
	v_add_f32_dpp v104, v150, v150 row_mirror row_mask:0xf bank_mask:0x3 bound_ctrl:1
	v_add_f32_dpp v104, v158, v158 row_mirror row_mask:0xf bank_mask:0xc bound_ctrl:1
	v_add_f32_dpp v105, v151, v151 row_mirror row_mask:0xf bank_mask:0x3 bound_ctrl:1
	v_add_f32_dpp v105, v159, v159 row_mirror row_mask:0xf bank_mask:0xc bound_ctrl:1
	v_add_f32_dpp v106, v152, v152 row_mirror row_mask:0xf bank_mask:0x3 bound_ctrl:1
	v_add_f32_dpp v106, v160, v160 row_mirror row_mask:0xf bank_mask:0xc bound_ctrl:1
	v_add_f32_dpp v107, v153, v153 row_mirror row_mask:0xf bank_mask:0x3 bound_ctrl:1
	v_add_f32_dpp v107, v161, v161 row_mirror row_mask:0xf bank_mask:0xc bound_ctrl:1
	v_add_f32_dpp v108, v154, v154 row_mirror row_mask:0xf bank_mask:0x3 bound_ctrl:1
	v_add_f32_dpp v108, v162, v162 row_mirror row_mask:0xf bank_mask:0xc bound_ctrl:1
	v_add_f32_dpp v109, v155, v155 row_mirror row_mask:0xf bank_mask:0x3 bound_ctrl:1
	v_add_f32_dpp v109, v163, v163 row_mirror row_mask:0xf bank_mask:0xc bound_ctrl:1
	v_add_f32_dpp v110, v102, v102 row_half_mirror row_mask:0xf bank_mask:0x5 bound_ctrl:1
	v_add_f32_dpp v110, v106, v106 row_half_mirror row_mask:0xf bank_mask:0xa bound_ctrl:1
	v_add_f32_dpp v111, v103, v103 row_half_mirror row_mask:0xf bank_mask:0x5 bound_ctrl:1
	v_add_f32_dpp v111, v107, v107 row_half_mirror row_mask:0xf bank_mask:0xa bound_ctrl:1
	v_add_f32_dpp v112, v104, v104 row_half_mirror row_mask:0xf bank_mask:0x5 bound_ctrl:1
	v_add_f32_dpp v112, v108, v108 row_half_mirror row_mask:0xf bank_mask:0xa bound_ctrl:1
	v_add_f32_dpp v113, v105, v105 row_half_mirror row_mask:0xf bank_mask:0x5 bound_ctrl:1
	v_add_f32_dpp v113, v109, v109 row_half_mirror row_mask:0xf bank_mask:0xa bound_ctrl:1
	s_mov_b32 vcc_lo, 0xcccccccc
	s_mov_b32 vcc_hi, 0xcccccccc
	v_cndmask_b32 v116, v112, v110, vcc
	v_cndmask_b32 v117, v113, v111, vcc
	v_cndmask_b32 v114, v110, v112, vcc
	v_cndmask_b32 v115, v111, v113, vcc
	v_add_f32_dpp v114, v116, v114 quad_perm:[2,3,0,1] row_mask:0xf bank_mask:0xf bound_ctrl:1
	v_add_f32_dpp v115, v117, v115 quad_perm:[2,3,0,1] row_mask:0xf bank_mask:0xf bound_ctrl:1
	s_mov_b32 vcc_lo, 0xaaaaaaaa
	s_mov_b32 vcc_hi, 0xaaaaaaaa
	v_cndmask_b32 v116, v115, v114, vcc
	v_cndmask_b32 v117, v114, v115, vcc
	s_nop 0
	v_add_f32_dpp v18, v116, v117 quad_perm:[1,0,3,2] row_mask:0xf bank_mask:0xf bound_ctrl:1
	v_add_f32_dpp v146, v146, v146 quad_perm:[1,0,3,2] row_mask:0xf bank_mask:0xf bound_ctrl:1
	v_pk_mul_f32 v[180:181], v[138:139], v[180:181]
	v_pk_fma_f32 v[180:181], v[140:141], v[182:183], v[180:181]
	v_add_f32_dpp v146, v146, v146 quad_perm:[2,3,0,1] row_mask:0xf bank_mask:0xf bound_ctrl:1
	s_waitcnt lgkmcnt(12)
	v_pk_mul_f32 v[198:199], v[198:199], v[206:207] op_sel_hi:[1,0]
	v_add_f32_dpp v146, v146, v146 row_half_mirror row_mask:0xf bank_mask:0xf bound_ctrl:1
	v_pk_mul_f32 v[200:201], v[200:201], v[206:207] op_sel_hi:[1,0]
	v_add_f32 v148, v180, v181
	v_add_f32_dpp v146, v146, v146 row_mirror row_mask:0xf bank_mask:0xf bound_ctrl:1
	v_pk_fma_f32 v[198:199], v[146:147], v[190:191], v[198:199] op_sel_hi:[0,1,1] neg_lo:[1,0,0] neg_hi:[1,0,0]
	v_pk_fma_f32 v[200:201], v[146:147], v[192:193], v[200:201] op_sel_hi:[0,1,1] neg_lo:[1,0,0] neg_hi:[1,0,0]
	v_pk_fma_f32 v[138:139], v[138:139], v[194:195], v[198:199]
	v_pk_fma_f32 v[140:141], v[140:141], v[196:197], v[200:201]
	v_pk_mul_f32 v[144:145], v[138:139], v[208:209]
	v_pk_fma_f32 v[144:145], v[140:141], v[210:211], v[144:145]
	v_add_f32 v146, v144, v145
	ds_read_b128 v[168:171], v10 offset:30976
	ds_read_b128 v[172:175], v10 offset:31232
	ds_read_b128 v[176:179], v10 offset:31488
	ds_read_b128 v[180:183], v10 offset:31744
	ds_read_b32 v184, v11 offset:30720
	ds_read_b128 v[186:189], v10 offset:32256
	v_add_f32_dpp v146, v146, v146 quad_perm:[1,0,3,2] row_mask:0xf bank_mask:0xf bound_ctrl:1
	v_pk_mul_f32 v[202:203], v[138:139], v[202:203]
	v_pk_fma_f32 v[202:203], v[140:141], v[204:205], v[202:203]
	v_add_f32_dpp v146, v146, v146 quad_perm:[2,3,0,1] row_mask:0xf bank_mask:0xf bound_ctrl:1
	s_waitcnt lgkmcnt(12)
	v_pk_mul_f32 v[220:221], v[220:221], v[228:229] op_sel_hi:[1,0]
	v_add_f32_dpp v146, v146, v146 row_half_mirror row_mask:0xf bank_mask:0xf bound_ctrl:1
	v_pk_mul_f32 v[222:223], v[222:223], v[228:229] op_sel_hi:[1,0]
	v_add_f32 v149, v202, v203
	v_add_f32_dpp v146, v146, v146 row_mirror row_mask:0xf bank_mask:0xf bound_ctrl:1
	v_pk_fma_f32 v[220:221], v[146:147], v[212:213], v[220:221] op_sel_hi:[0,1,1] neg_lo:[1,0,0] neg_hi:[1,0,0]
	v_pk_fma_f32 v[222:223], v[146:147], v[214:215], v[222:223] op_sel_hi:[0,1,1] neg_lo:[1,0,0] neg_hi:[1,0,0]
	v_pk_fma_f32 v[138:139], v[138:139], v[216:217], v[220:221]
	v_pk_fma_f32 v[140:141], v[140:141], v[218:219], v[222:223]
	v_pk_mul_f32 v[144:145], v[138:139], v[230:231]
	v_pk_fma_f32 v[144:145], v[140:141], v[232:233], v[144:145]
	v_add_f32 v146, v144, v145
	ds_read_b128 v[190:193], v10 offset:32512
	ds_read_b128 v[194:197], v10 offset:32768
	ds_read_b128 v[198:201], v10 offset:33024
	ds_read_b128 v[202:205], v10 offset:33280
	ds_read_b32 v206, v11 offset:32256
	ds_read_b128 v[208:211], v10 offset:33792
	v_add_f32_dpp v146, v146, v146 quad_perm:[1,0,3,2] row_mask:0xf bank_mask:0xf bound_ctrl:1
	v_pk_mul_f32 v[224:225], v[138:139], v[224:225]
	v_pk_fma_f32 v[224:225], v[140:141], v[226:227], v[224:225]
	v_add_f32_dpp v146, v146, v146 quad_perm:[2,3,0,1] row_mask:0xf bank_mask:0xf bound_ctrl:1
	s_waitcnt lgkmcnt(12)
	v_pk_mul_f32 v[242:243], v[242:243], v[250:251] op_sel_hi:[1,0]
	v_add_f32_dpp v146, v146, v146 row_half_mirror row_mask:0xf bank_mask:0xf bound_ctrl:1
	v_pk_mul_f32 v[244:245], v[244:245], v[250:251] op_sel_hi:[1,0]
	v_add_f32 v150, v224, v225
	v_add_f32_dpp v146, v146, v146 row_mirror row_mask:0xf bank_mask:0xf bound_ctrl:1
	v_pk_fma_f32 v[242:243], v[146:147], v[234:235], v[242:243] op_sel_hi:[0,1,1] neg_lo:[1,0,0] neg_hi:[1,0,0]
	v_pk_fma_f32 v[244:245], v[146:147], v[236:237], v[244:245] op_sel_hi:[0,1,1] neg_lo:[1,0,0] neg_hi:[1,0,0]
	v_pk_fma_f32 v[138:139], v[138:139], v[238:239], v[242:243]
	v_pk_fma_f32 v[140:141], v[140:141], v[240:241], v[244:245]
	v_pk_mul_f32 v[144:145], v[138:139], v[164:165]
	v_pk_fma_f32 v[144:145], v[140:141], v[166:167], v[144:145]
	v_add_f32 v146, v144, v145
	ds_read_b128 v[212:215], v10 offset:34048
	ds_read_b128 v[216:219], v10 offset:34304
	ds_read_b128 v[220:223], v10 offset:34560
	ds_read_b128 v[224:227], v10 offset:34816
	ds_read_b32 v228, v11 offset:33792
	ds_read_b128 v[230:233], v10 offset:35328
	v_add_f32_dpp v146, v146, v146 quad_perm:[1,0,3,2] row_mask:0xf bank_mask:0xf bound_ctrl:1
	v_pk_mul_f32 v[246:247], v[138:139], v[246:247]
	v_pk_fma_f32 v[246:247], v[140:141], v[248:249], v[246:247]
	v_add_f32_dpp v146, v146, v146 quad_perm:[2,3,0,1] row_mask:0xf bank_mask:0xf bound_ctrl:1
	s_waitcnt lgkmcnt(12)
	v_pk_mul_f32 v[176:177], v[176:177], v[184:185] op_sel_hi:[1,0]
	v_add_f32_dpp v146, v146, v146 row_half_mirror row_mask:0xf bank_mask:0xf bound_ctrl:1
	v_pk_mul_f32 v[178:179], v[178:179], v[184:185] op_sel_hi:[1,0]
	v_add_f32 v151, v246, v247
	v_add_f32_dpp v146, v146, v146 row_mirror row_mask:0xf bank_mask:0xf bound_ctrl:1
	v_pk_fma_f32 v[176:177], v[146:147], v[168:169], v[176:177] op_sel_hi:[0,1,1] neg_lo:[1,0,0] neg_hi:[1,0,0]
	v_pk_fma_f32 v[178:179], v[146:147], v[170:171], v[178:179] op_sel_hi:[0,1,1] neg_lo:[1,0,0] neg_hi:[1,0,0]
	v_pk_fma_f32 v[138:139], v[138:139], v[172:173], v[176:177]
	v_pk_fma_f32 v[140:141], v[140:141], v[174:175], v[178:179]
	v_pk_mul_f32 v[144:145], v[138:139], v[186:187]
	v_pk_fma_f32 v[144:145], v[140:141], v[188:189], v[144:145]
	v_add_f32 v146, v144, v145
	ds_read_b128 v[234:237], v10 offset:35584
	ds_read_b128 v[238:241], v10 offset:35840
	ds_read_b128 v[242:245], v10 offset:36096
	ds_read_b128 v[246:249], v10 offset:36352
	ds_read_b32 v250, v11 offset:35328
	ds_read_b128 v[164:167], v10 offset:36864
	v_add_f32_dpp v146, v146, v146 quad_perm:[1,0,3,2] row_mask:0xf bank_mask:0xf bound_ctrl:1
	v_pk_mul_f32 v[180:181], v[138:139], v[180:181]
	v_pk_fma_f32 v[180:181], v[140:141], v[182:183], v[180:181]
	v_add_f32_dpp v146, v146, v146 quad_perm:[2,3,0,1] row_mask:0xf bank_mask:0xf bound_ctrl:1
	s_waitcnt lgkmcnt(12)
	v_pk_mul_f32 v[198:199], v[198:199], v[206:207] op_sel_hi:[1,0]
	v_add_f32_dpp v146, v146, v146 row_half_mirror row_mask:0xf bank_mask:0xf bound_ctrl:1
	v_pk_mul_f32 v[200:201], v[200:201], v[206:207] op_sel_hi:[1,0]
	v_add_f32 v152, v180, v181
	v_add_f32_dpp v146, v146, v146 row_mirror row_mask:0xf bank_mask:0xf bound_ctrl:1
	v_pk_fma_f32 v[198:199], v[146:147], v[190:191], v[198:199] op_sel_hi:[0,1,1] neg_lo:[1,0,0] neg_hi:[1,0,0]
	v_pk_fma_f32 v[200:201], v[146:147], v[192:193], v[200:201] op_sel_hi:[0,1,1] neg_lo:[1,0,0] neg_hi:[1,0,0]
	v_pk_fma_f32 v[138:139], v[138:139], v[194:195], v[198:199]
	v_pk_fma_f32 v[140:141], v[140:141], v[196:197], v[200:201]
	v_pk_mul_f32 v[144:145], v[138:139], v[208:209]
	v_pk_fma_f32 v[144:145], v[140:141], v[210:211], v[144:145]
	v_add_f32 v146, v144, v145
	ds_read_b128 v[168:171], v10 offset:37120
	ds_read_b128 v[172:175], v10 offset:37376
	ds_read_b128 v[176:179], v10 offset:37632
	ds_read_b128 v[180:183], v10 offset:37888
	ds_read_b32 v184, v11 offset:36864
	ds_read_b128 v[186:189], v10 offset:38400
	v_add_f32_dpp v146, v146, v146 quad_perm:[1,0,3,2] row_mask:0xf bank_mask:0xf bound_ctrl:1
	v_pk_mul_f32 v[202:203], v[138:139], v[202:203]
	v_pk_fma_f32 v[202:203], v[140:141], v[204:205], v[202:203]
	v_add_f32_dpp v146, v146, v146 quad_perm:[2,3,0,1] row_mask:0xf bank_mask:0xf bound_ctrl:1
	s_waitcnt lgkmcnt(12)
	v_pk_mul_f32 v[220:221], v[220:221], v[228:229] op_sel_hi:[1,0]
	v_add_f32_dpp v146, v146, v146 row_half_mirror row_mask:0xf bank_mask:0xf bound_ctrl:1
	v_pk_mul_f32 v[222:223], v[222:223], v[228:229] op_sel_hi:[1,0]
	v_add_f32 v153, v202, v203
	v_add_f32_dpp v146, v146, v146 row_mirror row_mask:0xf bank_mask:0xf bound_ctrl:1
	v_pk_fma_f32 v[220:221], v[146:147], v[212:213], v[220:221] op_sel_hi:[0,1,1] neg_lo:[1,0,0] neg_hi:[1,0,0]
	v_pk_fma_f32 v[222:223], v[146:147], v[214:215], v[222:223] op_sel_hi:[0,1,1] neg_lo:[1,0,0] neg_hi:[1,0,0]
	v_pk_fma_f32 v[138:139], v[138:139], v[216:217], v[220:221]
	v_pk_fma_f32 v[140:141], v[140:141], v[218:219], v[222:223]
	v_pk_mul_f32 v[144:145], v[138:139], v[230:231]
	v_pk_fma_f32 v[144:145], v[140:141], v[232:233], v[144:145]
	v_add_f32 v146, v144, v145
	ds_read_b128 v[190:193], v10 offset:38656
	ds_read_b128 v[194:197], v10 offset:38912
	ds_read_b128 v[198:201], v10 offset:39168
	ds_read_b128 v[202:205], v10 offset:39424
	ds_read_b32 v206, v11 offset:38400
	ds_read_b128 v[208:211], v10 offset:39936
	v_add_f32_dpp v146, v146, v146 quad_perm:[1,0,3,2] row_mask:0xf bank_mask:0xf bound_ctrl:1
	v_pk_mul_f32 v[224:225], v[138:139], v[224:225]
	v_pk_fma_f32 v[224:225], v[140:141], v[226:227], v[224:225]
	v_add_f32_dpp v146, v146, v146 quad_perm:[2,3,0,1] row_mask:0xf bank_mask:0xf bound_ctrl:1
	s_waitcnt lgkmcnt(12)
	v_pk_mul_f32 v[242:243], v[242:243], v[250:251] op_sel_hi:[1,0]
	v_add_f32_dpp v146, v146, v146 row_half_mirror row_mask:0xf bank_mask:0xf bound_ctrl:1
	v_pk_mul_f32 v[244:245], v[244:245], v[250:251] op_sel_hi:[1,0]
	v_add_f32 v154, v224, v225
	v_add_f32_dpp v146, v146, v146 row_mirror row_mask:0xf bank_mask:0xf bound_ctrl:1
	v_pk_fma_f32 v[242:243], v[146:147], v[234:235], v[242:243] op_sel_hi:[0,1,1] neg_lo:[1,0,0] neg_hi:[1,0,0]
	v_pk_fma_f32 v[244:245], v[146:147], v[236:237], v[244:245] op_sel_hi:[0,1,1] neg_lo:[1,0,0] neg_hi:[1,0,0]
	v_pk_fma_f32 v[138:139], v[138:139], v[238:239], v[242:243]
	v_pk_fma_f32 v[140:141], v[140:141], v[240:241], v[244:245]
	v_pk_mul_f32 v[144:145], v[138:139], v[164:165]
	v_pk_fma_f32 v[144:145], v[140:141], v[166:167], v[144:145]
	v_add_f32 v146, v144, v145
	ds_read_b128 v[212:215], v10 offset:40192
	ds_read_b128 v[216:219], v10 offset:40448
	ds_read_b128 v[220:223], v10 offset:40704
	ds_read_b128 v[224:227], v10 offset:40960
	ds_read_b32 v228, v11 offset:39936
	ds_read_b128 v[230:233], v10 offset:41472
	v_add_f32_dpp v146, v146, v146 quad_perm:[1,0,3,2] row_mask:0xf bank_mask:0xf bound_ctrl:1
	v_pk_mul_f32 v[246:247], v[138:139], v[246:247]
	v_pk_fma_f32 v[246:247], v[140:141], v[248:249], v[246:247]
	v_add_f32_dpp v146, v146, v146 quad_perm:[2,3,0,1] row_mask:0xf bank_mask:0xf bound_ctrl:1
	s_waitcnt lgkmcnt(12)
	v_pk_mul_f32 v[176:177], v[176:177], v[184:185] op_sel_hi:[1,0]
	v_add_f32_dpp v146, v146, v146 row_half_mirror row_mask:0xf bank_mask:0xf bound_ctrl:1
	v_pk_mul_f32 v[178:179], v[178:179], v[184:185] op_sel_hi:[1,0]
	v_add_f32 v155, v246, v247
	v_add_f32_dpp v146, v146, v146 row_mirror row_mask:0xf bank_mask:0xf bound_ctrl:1
	v_pk_fma_f32 v[176:177], v[146:147], v[168:169], v[176:177] op_sel_hi:[0,1,1] neg_lo:[1,0,0] neg_hi:[1,0,0]
	v_pk_fma_f32 v[178:179], v[146:147], v[170:171], v[178:179] op_sel_hi:[0,1,1] neg_lo:[1,0,0] neg_hi:[1,0,0]
	v_pk_fma_f32 v[138:139], v[138:139], v[172:173], v[176:177]
	v_pk_fma_f32 v[140:141], v[140:141], v[174:175], v[178:179]
	v_pk_mul_f32 v[144:145], v[138:139], v[186:187]
	v_pk_fma_f32 v[144:145], v[140:141], v[188:189], v[144:145]
	v_add_f32 v146, v144, v145
	ds_read_b128 v[234:237], v10 offset:41728
	ds_read_b128 v[238:241], v10 offset:41984
	ds_read_b128 v[242:245], v10 offset:42240
	ds_read_b128 v[246:249], v10 offset:42496
	ds_read_b32 v250, v11 offset:41472
	ds_read_b128 v[164:167], v10 offset:43008
	v_add_f32_dpp v146, v146, v146 quad_perm:[1,0,3,2] row_mask:0xf bank_mask:0xf bound_ctrl:1
	v_pk_mul_f32 v[180:181], v[138:139], v[180:181]
	v_pk_fma_f32 v[180:181], v[140:141], v[182:183], v[180:181]
	v_add_f32_dpp v146, v146, v146 quad_perm:[2,3,0,1] row_mask:0xf bank_mask:0xf bound_ctrl:1
	s_waitcnt lgkmcnt(12)
	v_pk_mul_f32 v[198:199], v[198:199], v[206:207] op_sel_hi:[1,0]
	v_add_f32_dpp v146, v146, v146 row_half_mirror row_mask:0xf bank_mask:0xf bound_ctrl:1
	v_pk_mul_f32 v[200:201], v[200:201], v[206:207] op_sel_hi:[1,0]
	v_add_f32 v156, v180, v181
	v_add_f32_dpp v146, v146, v146 row_mirror row_mask:0xf bank_mask:0xf bound_ctrl:1
	v_pk_fma_f32 v[198:199], v[146:147], v[190:191], v[198:199] op_sel_hi:[0,1,1] neg_lo:[1,0,0] neg_hi:[1,0,0]
	v_pk_fma_f32 v[200:201], v[146:147], v[192:193], v[200:201] op_sel_hi:[0,1,1] neg_lo:[1,0,0] neg_hi:[1,0,0]
	v_pk_fma_f32 v[138:139], v[138:139], v[194:195], v[198:199]
	v_pk_fma_f32 v[140:141], v[140:141], v[196:197], v[200:201]
	v_pk_mul_f32 v[144:145], v[138:139], v[208:209]
	v_pk_fma_f32 v[144:145], v[140:141], v[210:211], v[144:145]
	v_add_f32 v146, v144, v145
	ds_read_b128 v[168:171], v10 offset:43264
	ds_read_b128 v[172:175], v10 offset:43520
	ds_read_b128 v[176:179], v10 offset:43776
	ds_read_b128 v[180:183], v10 offset:44032
	ds_read_b32 v184, v11 offset:43008
	ds_read_b128 v[186:189], v10 offset:44544
	v_add_f32_dpp v146, v146, v146 quad_perm:[1,0,3,2] row_mask:0xf bank_mask:0xf bound_ctrl:1
	v_pk_mul_f32 v[202:203], v[138:139], v[202:203]
	v_pk_fma_f32 v[202:203], v[140:141], v[204:205], v[202:203]
	v_add_f32_dpp v146, v146, v146 quad_perm:[2,3,0,1] row_mask:0xf bank_mask:0xf bound_ctrl:1
	s_waitcnt lgkmcnt(12)
	v_pk_mul_f32 v[220:221], v[220:221], v[228:229] op_sel_hi:[1,0]
	v_add_f32_dpp v146, v146, v146 row_half_mirror row_mask:0xf bank_mask:0xf bound_ctrl:1
	v_pk_mul_f32 v[222:223], v[222:223], v[228:229] op_sel_hi:[1,0]
	v_add_f32 v157, v202, v203
	v_add_f32_dpp v146, v146, v146 row_mirror row_mask:0xf bank_mask:0xf bound_ctrl:1
	v_pk_fma_f32 v[220:221], v[146:147], v[212:213], v[220:221] op_sel_hi:[0,1,1] neg_lo:[1,0,0] neg_hi:[1,0,0]
	v_pk_fma_f32 v[222:223], v[146:147], v[214:215], v[222:223] op_sel_hi:[0,1,1] neg_lo:[1,0,0] neg_hi:[1,0,0]
	v_pk_fma_f32 v[138:139], v[138:139], v[216:217], v[220:221]
	v_pk_fma_f32 v[140:141], v[140:141], v[218:219], v[222:223]
	v_pk_mul_f32 v[144:145], v[138:139], v[230:231]
	v_pk_fma_f32 v[144:145], v[140:141], v[232:233], v[144:145]
	v_add_f32 v146, v144, v145
	ds_read_b128 v[190:193], v10 offset:44800
	ds_read_b128 v[194:197], v10 offset:45056
	ds_read_b128 v[198:201], v10 offset:45312
	ds_read_b128 v[202:205], v10 offset:45568
	ds_read_b32 v206, v11 offset:44544
	ds_read_b128 v[208:211], v10 offset:46080
	v_add_f32_dpp v146, v146, v146 quad_perm:[1,0,3,2] row_mask:0xf bank_mask:0xf bound_ctrl:1
	v_pk_mul_f32 v[224:225], v[138:139], v[224:225]
	v_pk_fma_f32 v[224:225], v[140:141], v[226:227], v[224:225]
	v_add_f32_dpp v146, v146, v146 quad_perm:[2,3,0,1] row_mask:0xf bank_mask:0xf bound_ctrl:1
	s_waitcnt lgkmcnt(12)
	v_pk_mul_f32 v[242:243], v[242:243], v[250:251] op_sel_hi:[1,0]
	v_add_f32_dpp v146, v146, v146 row_half_mirror row_mask:0xf bank_mask:0xf bound_ctrl:1
	v_pk_mul_f32 v[244:245], v[244:245], v[250:251] op_sel_hi:[1,0]
	v_add_f32 v158, v224, v225
	v_add_f32_dpp v146, v146, v146 row_mirror row_mask:0xf bank_mask:0xf bound_ctrl:1
	v_pk_fma_f32 v[242:243], v[146:147], v[234:235], v[242:243] op_sel_hi:[0,1,1] neg_lo:[1,0,0] neg_hi:[1,0,0]
	v_pk_fma_f32 v[244:245], v[146:147], v[236:237], v[244:245] op_sel_hi:[0,1,1] neg_lo:[1,0,0] neg_hi:[1,0,0]
	v_pk_fma_f32 v[138:139], v[138:139], v[238:239], v[242:243]
	v_pk_fma_f32 v[140:141], v[140:141], v[240:241], v[244:245]
	v_pk_mul_f32 v[144:145], v[138:139], v[164:165]
	v_pk_fma_f32 v[144:145], v[140:141], v[166:167], v[144:145]
	v_add_f32 v146, v144, v145
	ds_read_b128 v[212:215], v10 offset:46336
	ds_read_b128 v[216:219], v10 offset:46592
	ds_read_b128 v[220:223], v10 offset:46848
	ds_read_b128 v[224:227], v10 offset:47104
	ds_read_b32 v228, v11 offset:46080
	ds_read_b128 v[230:233], v10 offset:47616
	v_add_f32_dpp v146, v146, v146 quad_perm:[1,0,3,2] row_mask:0xf bank_mask:0xf bound_ctrl:1
	v_pk_mul_f32 v[246:247], v[138:139], v[246:247]
	v_pk_fma_f32 v[246:247], v[140:141], v[248:249], v[246:247]
	v_add_f32_dpp v146, v146, v146 quad_perm:[2,3,0,1] row_mask:0xf bank_mask:0xf bound_ctrl:1
	s_waitcnt lgkmcnt(12)
	v_pk_mul_f32 v[176:177], v[176:177], v[184:185] op_sel_hi:[1,0]
	v_add_f32_dpp v146, v146, v146 row_half_mirror row_mask:0xf bank_mask:0xf bound_ctrl:1
	v_pk_mul_f32 v[178:179], v[178:179], v[184:185] op_sel_hi:[1,0]
	v_add_f32 v159, v246, v247
	v_add_f32_dpp v146, v146, v146 row_mirror row_mask:0xf bank_mask:0xf bound_ctrl:1
	v_pk_fma_f32 v[176:177], v[146:147], v[168:169], v[176:177] op_sel_hi:[0,1,1] neg_lo:[1,0,0] neg_hi:[1,0,0]
	v_pk_fma_f32 v[178:179], v[146:147], v[170:171], v[178:179] op_sel_hi:[0,1,1] neg_lo:[1,0,0] neg_hi:[1,0,0]
	v_pk_fma_f32 v[138:139], v[138:139], v[172:173], v[176:177]
	v_pk_fma_f32 v[140:141], v[140:141], v[174:175], v[178:179]
	v_pk_mul_f32 v[144:145], v[138:139], v[186:187]
	v_pk_fma_f32 v[144:145], v[140:141], v[188:189], v[144:145]
	v_add_f32 v146, v144, v145
	ds_read_b128 v[234:237], v10 offset:47872
	ds_read_b128 v[238:241], v10 offset:48128
	ds_read_b128 v[242:245], v10 offset:48384
	ds_read_b128 v[246:249], v10 offset:48640
	ds_read_b32 v250, v11 offset:47616
	v_add_f32_dpp v146, v146, v146 quad_perm:[1,0,3,2] row_mask:0xf bank_mask:0xf bound_ctrl:1
	v_pk_mul_f32 v[180:181], v[138:139], v[180:181]
	v_pk_fma_f32 v[180:181], v[140:141], v[182:183], v[180:181]
	v_add_f32_dpp v146, v146, v146 quad_perm:[2,3,0,1] row_mask:0xf bank_mask:0xf bound_ctrl:1
	s_waitcnt lgkmcnt(11)
	v_pk_mul_f32 v[198:199], v[198:199], v[206:207] op_sel_hi:[1,0]
	v_add_f32_dpp v146, v146, v146 row_half_mirror row_mask:0xf bank_mask:0xf bound_ctrl:1
	v_pk_mul_f32 v[200:201], v[200:201], v[206:207] op_sel_hi:[1,0]
	v_add_f32 v160, v180, v181
	v_add_f32_dpp v146, v146, v146 row_mirror row_mask:0xf bank_mask:0xf bound_ctrl:1
	v_pk_fma_f32 v[198:199], v[146:147], v[190:191], v[198:199] op_sel_hi:[0,1,1] neg_lo:[1,0,0] neg_hi:[1,0,0]
	v_pk_fma_f32 v[200:201], v[146:147], v[192:193], v[200:201] op_sel_hi:[0,1,1] neg_lo:[1,0,0] neg_hi:[1,0,0]
	v_pk_fma_f32 v[138:139], v[138:139], v[194:195], v[198:199]
	v_pk_fma_f32 v[140:141], v[140:141], v[196:197], v[200:201]
	v_pk_mul_f32 v[144:145], v[138:139], v[208:209]
	v_pk_fma_f32 v[144:145], v[140:141], v[210:211], v[144:145]
	v_add_f32 v146, v144, v145
	s_nop 1
	v_add_f32_dpp v146, v146, v146 quad_perm:[1,0,3,2] row_mask:0xf bank_mask:0xf bound_ctrl:1
	v_pk_mul_f32 v[202:203], v[138:139], v[202:203]
	v_pk_fma_f32 v[202:203], v[140:141], v[204:205], v[202:203]
	v_add_f32_dpp v146, v146, v146 quad_perm:[2,3,0,1] row_mask:0xf bank_mask:0xf bound_ctrl:1
	s_waitcnt lgkmcnt(5)
	v_pk_mul_f32 v[220:221], v[220:221], v[228:229] op_sel_hi:[1,0]
	v_add_f32_dpp v146, v146, v146 row_half_mirror row_mask:0xf bank_mask:0xf bound_ctrl:1
	v_pk_mul_f32 v[222:223], v[222:223], v[228:229] op_sel_hi:[1,0]
	v_add_f32 v161, v202, v203
	v_add_f32_dpp v146, v146, v146 row_mirror row_mask:0xf bank_mask:0xf bound_ctrl:1
	v_pk_fma_f32 v[220:221], v[146:147], v[212:213], v[220:221] op_sel_hi:[0,1,1] neg_lo:[1,0,0] neg_hi:[1,0,0]
	v_pk_fma_f32 v[222:223], v[146:147], v[214:215], v[222:223] op_sel_hi:[0,1,1] neg_lo:[1,0,0] neg_hi:[1,0,0]
	v_pk_fma_f32 v[138:139], v[138:139], v[216:217], v[220:221]
	v_pk_fma_f32 v[140:141], v[140:141], v[218:219], v[222:223]
	v_pk_mul_f32 v[144:145], v[138:139], v[230:231]
	v_pk_fma_f32 v[144:145], v[140:141], v[232:233], v[144:145]
	v_add_f32 v146, v144, v145
	s_nop 1
	v_add_f32_dpp v146, v146, v146 quad_perm:[1,0,3,2] row_mask:0xf bank_mask:0xf bound_ctrl:1
	v_pk_mul_f32 v[224:225], v[138:139], v[224:225]
	v_pk_fma_f32 v[224:225], v[140:141], v[226:227], v[224:225]
	v_add_f32_dpp v146, v146, v146 quad_perm:[2,3,0,1] row_mask:0xf bank_mask:0xf bound_ctrl:1
	s_waitcnt lgkmcnt(0)
	v_pk_mul_f32 v[242:243], v[242:243], v[250:251] op_sel_hi:[1,0]
	v_add_f32_dpp v146, v146, v146 row_half_mirror row_mask:0xf bank_mask:0xf bound_ctrl:1
	v_pk_mul_f32 v[244:245], v[244:245], v[250:251] op_sel_hi:[1,0]
	v_add_f32 v162, v224, v225
	v_add_f32_dpp v146, v146, v146 row_mirror row_mask:0xf bank_mask:0xf bound_ctrl:1
	v_pk_fma_f32 v[242:243], v[146:147], v[234:235], v[242:243] op_sel_hi:[0,1,1] neg_lo:[1,0,0] neg_hi:[1,0,0]
	v_pk_fma_f32 v[244:245], v[146:147], v[236:237], v[244:245] op_sel_hi:[0,1,1] neg_lo:[1,0,0] neg_hi:[1,0,0]
	v_pk_fma_f32 v[138:139], v[138:139], v[238:239], v[242:243]
	v_pk_fma_f32 v[140:141], v[140:141], v[240:241], v[244:245]
	v_pk_mul_f32 v[246:247], v[138:139], v[246:247]
	v_pk_fma_f32 v[246:247], v[140:141], v[248:249], v[246:247]
	v_add_f32 v163, v246, v247
	s_nop 0
	v_add_f32_dpp v102, v148, v148 row_mirror row_mask:0xf bank_mask:0x3 bound_ctrl:1
	v_add_f32_dpp v102, v156, v156 row_mirror row_mask:0xf bank_mask:0xc bound_ctrl:1
	v_add_f32_dpp v103, v149, v149 row_mirror row_mask:0xf bank_mask:0x3 bound_ctrl:1
	v_add_f32_dpp v103, v157, v157 row_mirror row_mask:0xf bank_mask:0xc bound_ctrl:1
	v_add_f32_dpp v104, v150, v150 row_mirror row_mask:0xf bank_mask:0x3 bound_ctrl:1
	v_add_f32_dpp v104, v158, v158 row_mirror row_mask:0xf bank_mask:0xc bound_ctrl:1
	v_add_f32_dpp v105, v151, v151 row_mirror row_mask:0xf bank_mask:0x3 bound_ctrl:1
	v_add_f32_dpp v105, v159, v159 row_mirror row_mask:0xf bank_mask:0xc bound_ctrl:1
	v_add_f32_dpp v106, v152, v152 row_mirror row_mask:0xf bank_mask:0x3 bound_ctrl:1
	v_add_f32_dpp v106, v160, v160 row_mirror row_mask:0xf bank_mask:0xc bound_ctrl:1
	v_add_f32_dpp v107, v153, v153 row_mirror row_mask:0xf bank_mask:0x3 bound_ctrl:1
	v_add_f32_dpp v107, v161, v161 row_mirror row_mask:0xf bank_mask:0xc bound_ctrl:1
	v_add_f32_dpp v108, v154, v154 row_mirror row_mask:0xf bank_mask:0x3 bound_ctrl:1
	v_add_f32_dpp v108, v162, v162 row_mirror row_mask:0xf bank_mask:0xc bound_ctrl:1
	v_add_f32_dpp v109, v155, v155 row_mirror row_mask:0xf bank_mask:0x3 bound_ctrl:1
	v_add_f32_dpp v109, v163, v163 row_mirror row_mask:0xf bank_mask:0xc bound_ctrl:1
	v_add_f32_dpp v110, v102, v102 row_half_mirror row_mask:0xf bank_mask:0x5 bound_ctrl:1
	v_add_f32_dpp v110, v106, v106 row_half_mirror row_mask:0xf bank_mask:0xa bound_ctrl:1
	v_add_f32_dpp v111, v103, v103 row_half_mirror row_mask:0xf bank_mask:0x5 bound_ctrl:1
	v_add_f32_dpp v111, v107, v107 row_half_mirror row_mask:0xf bank_mask:0xa bound_ctrl:1
	v_add_f32_dpp v112, v104, v104 row_half_mirror row_mask:0xf bank_mask:0x5 bound_ctrl:1
	v_add_f32_dpp v112, v108, v108 row_half_mirror row_mask:0xf bank_mask:0xa bound_ctrl:1
	v_add_f32_dpp v113, v105, v105 row_half_mirror row_mask:0xf bank_mask:0x5 bound_ctrl:1
	v_add_f32_dpp v113, v109, v109 row_half_mirror row_mask:0xf bank_mask:0xa bound_ctrl:1
	s_mov_b32 vcc_lo, 0xcccccccc
	s_mov_b32 vcc_hi, 0xcccccccc
	v_cndmask_b32 v116, v112, v110, vcc
	v_cndmask_b32 v117, v113, v111, vcc
	v_cndmask_b32 v114, v110, v112, vcc
	v_cndmask_b32 v115, v111, v113, vcc
	v_add_f32_dpp v114, v116, v114 quad_perm:[2,3,0,1] row_mask:0xf bank_mask:0xf bound_ctrl:1
	v_add_f32_dpp v115, v117, v115 quad_perm:[2,3,0,1] row_mask:0xf bank_mask:0xf bound_ctrl:1
	s_mov_b32 vcc_lo, 0xaaaaaaaa
	s_mov_b32 vcc_hi, 0xaaaaaaaa
	v_cndmask_b32 v116, v115, v114, vcc
	v_cndmask_b32 v117, v114, v115, vcc
	s_nop 0
	v_add_f32_dpp v19, v116, v117 quad_perm:[1,0,3,2] row_mask:0xf bank_mask:0xf bound_ctrl:1

; #define SCAN_BAR() asm volatile("s_barrier" ::: "memory")
; __device__ __forceinline__ void scan_unit(const Ctx& C0, const float* scn, int T, int quarter, const float* S0, float* Sout, unsigned char* obase, int mode) {
;     ...
;             if (mode == 0) { *(float*)(obase + (size_t)(k * 32 + q) * UPITCH_B + rl * 4) = osel0; *(float*)(obase + (size_t)(k * 32 + 16 + q) * UPITCH_B + rl * 4) = osel1; }
;             SCAN_BAR();
;         }
;         if (mode == 0) *(f32x4*)(Sout + irow * 64 + 4 * q) = (f32x4){S0x, S1x, S2x, S3x};
	s_addc_u32 s1, s1, 0
	v_add_co_u32_e32 v16, vcc, s8, v14
	s_cmp_lg_u32 s0, 0x5600000
	s_nop 0
	v_addc_co_u32_e32 v17, vcc, 0, v15, vcc
	v_add_co_u32_e32 v14, vcc, 0xfcaa000, v14
	global_store_dword v[16:17], v18, off offset:768
	s_nop 0
	v_addc_co_u32_e32 v15, vcc, 0, v15, vcc
	global_store_dword v[14:15], v19, off offset:768
	s_barrier
	s_cbranch_scc1 .LBB0_685
	v_mov_b32_e32 v2, v138
	v_mov_b32_e32 v13, v139
	v_mov_b32_e32 v12, v140
	v_mov_b32_e32 v8, v141
	v_readlane_b32 s0, v255, 46
	s_add_i32 s0, s3, s0
	s_ashr_i32 s1, s0, 31
	s_lshl_b64 s[0:1], s[0:1], 17
	v_readlane_b32 s3, v253, 26
	s_add_u32 s0, s3, s0
	v_readlane_b32 s3, v253, 27
	s_addc_u32 s1, s3, s1
	s_lshl_b32 s2, s2, 14
	s_add_u32 s0, s0, s2
	s_addc_u32 s1, s1, 0
	v_lshlrev_b32_e32 v0, 8, v0
	v_lshl_add_u64 v[6:7], s[0:1], 0, v[0:1]
	v_mov_b32_e32 v5, v1
	v_lshl_add_u64 v[6:7], v[6:7], 0, v[4:5]
	v_mov_b32_e32 v3, v13
	v_mov_b32_e32 v4, v12
	v_mov_b32_e32 v5, v8
	global_store_dwordx4 v[6:7], v[2:5], off
